# select threshold search: bracketed bisection starting at max (gallop max-2^24/27/30) instead of 32-bit bit-bisection
# speedup vs baseline: 1.0052x; 1.0052x over previous
; __device__ __forceinline__ void select_group(unsigned char* ws, int r0, const bf16_t* __restrict__ kib, int n, float* sc, SelPre& pre, int nr0, const bf16_t* __restrict__ nkib, int nn) {
;     ...
;     const float* rowl = sc + w * 4096 + lane;
;     const int nreg = (n + 63) >> 6;
;     const int nl = n - lane;
;     unsigned x[64];
; #pragma unroll
;     for (int i = 0; i < 64; ++i) {
;       const unsigned ub = __float_as_uint(rowl[i * 64]);
;       const unsigned o = ub ^ ((unsigned)((int)ub >> 31) | 0x80000000u);
;       x[i] = (i * 64 < nl) ? o : 0u;
;     }
;     unsigned tau = 0u;
;     int cge = 0;
;     switch ((nreg + 7) >> 3) {
.LBB0_2934:
	v_lshlrev_b32_e32 v16, 14, v206
	v_lshlrev_b32_e32 v115, 2, v114
	v_add3_u32 v16, 0, v16, v115
	ds_read2st64_b32 v[164:165], v16 offset1:1
	ds_read2st64_b32 v[166:167], v16 offset0:2 offset1:3
	ds_read2st64_b32 v[168:169], v16 offset0:4 offset1:5
	ds_read2st64_b32 v[170:171], v16 offset0:6 offset1:7
	v_sub_u32_e32 v240, s57, v114
	v_cmp_lt_i32_e32 vcc, s33, v240
	s_movk_i32 s0, 0x140
	s_waitcnt lgkmcnt(3)
	v_ashrrev_i32_e32 v115, 31, v164
	v_bitop3_b32 v239, v115, v164, s58 bitop3:0x36
	v_ashrrev_i32_e32 v115, 31, v165
	v_bitop3_b32 v238, v115, v165, s58 bitop3:0x36
	s_waitcnt lgkmcnt(2)
	v_ashrrev_i32_e32 v115, 31, v166
	v_bitop3_b32 v237, v115, v166, s58 bitop3:0x36
	v_ashrrev_i32_e32 v115, 31, v167
	v_bitop3_b32 v236, v115, v167, s58 bitop3:0x36
	s_waitcnt lgkmcnt(1)
	v_ashrrev_i32_e32 v115, 31, v168
	v_bitop3_b32 v115, v115, v168, s58 bitop3:0x36
	v_cndmask_b32_e32 v235, 0, v115, vcc
	v_ashrrev_i32_e32 v115, 31, v169
	v_bitop3_b32 v115, v115, v169, s58 bitop3:0x36
	v_cmp_lt_i32_e32 vcc, s0, v240
	ds_read2st64_b32 v[164:165], v16 offset0:8 offset1:9
	s_movk_i32 s0, 0x180
	v_cndmask_b32_e32 v234, 0, v115, vcc
	s_waitcnt lgkmcnt(1)
	v_ashrrev_i32_e32 v115, 31, v170
	v_bitop3_b32 v115, v115, v170, s58 bitop3:0x36
	v_cmp_lt_i32_e32 vcc, s0, v240
	s_movk_i32 s0, 0x1c0
	s_add_i32 s38, s57, 63
	v_cndmask_b32_e32 v233, 0, v115, vcc
	v_ashrrev_i32_e32 v115, 31, v171
	v_bitop3_b32 v115, v115, v171, s58 bitop3:0x36
	v_cmp_lt_i32_e32 vcc, s0, v240
	s_movk_i32 s0, 0x200
	ds_read2st64_b32 v[166:167], v16 offset0:10 offset1:11
	ds_read2st64_b32 v[168:169], v16 offset0:12 offset1:13
	ds_read2st64_b32 v[170:171], v16 offset0:14 offset1:15
	v_cndmask_b32_e32 v231, 0, v115, vcc
	s_waitcnt lgkmcnt(3)
	v_ashrrev_i32_e32 v115, 31, v164
	v_bitop3_b32 v115, v115, v164, s58 bitop3:0x36
	v_cmp_lt_i32_e32 vcc, s0, v240
	s_movk_i32 s0, 0x240
	s_lshr_b32 s38, s38, 6
	v_cndmask_b32_e32 v232, 0, v115, vcc
	v_ashrrev_i32_e32 v115, 31, v165
	v_bitop3_b32 v115, v115, v165, s58 bitop3:0x36
	v_cmp_lt_i32_e32 vcc, s0, v240
	s_movk_i32 s0, 0x280
	ds_read2st64_b32 v[164:165], v16 offset0:16 offset1:17
	v_cndmask_b32_e32 v230, 0, v115, vcc
	s_waitcnt lgkmcnt(3)
	v_ashrrev_i32_e32 v115, 31, v166
	v_bitop3_b32 v115, v115, v166, s58 bitop3:0x36
	v_cmp_lt_i32_e32 vcc, s0, v240
	s_movk_i32 s0, 0x2c0
	s_movk_i32 s10, 0xf80
	v_cndmask_b32_e32 v229, 0, v115, vcc
	v_ashrrev_i32_e32 v115, 31, v167
	v_bitop3_b32 v115, v115, v167, s58 bitop3:0x36
	v_cmp_lt_i32_e32 vcc, s0, v240
	s_movk_i32 s0, 0x300
	s_add_i32 s38, s38, 7
	v_cndmask_b32_e32 v228, 0, v115, vcc
	s_waitcnt lgkmcnt(2)
	v_ashrrev_i32_e32 v115, 31, v168
	v_bitop3_b32 v115, v115, v168, s58 bitop3:0x36
	v_cmp_lt_i32_e32 vcc, s0, v240
	s_movk_i32 s0, 0x340
	v_cmp_lt_i32_e64 s[14:15], s10, v240
	v_cndmask_b32_e32 v227, 0, v115, vcc
	v_ashrrev_i32_e32 v115, 31, v169
	v_bitop3_b32 v115, v115, v169, s58 bitop3:0x36
	v_cmp_lt_i32_e32 vcc, s0, v240
	s_movk_i32 s0, 0x380
	s_movk_i32 s10, 0xfc0
	v_cndmask_b32_e32 v226, 0, v115, vcc
	s_waitcnt lgkmcnt(1)
	v_ashrrev_i32_e32 v115, 31, v170
	v_bitop3_b32 v115, v115, v170, s58 bitop3:0x36
	v_cmp_lt_i32_e32 vcc, s0, v240
	s_movk_i32 s0, 0x3c0
	s_lshr_b32 s61, s38, 3
	v_cndmask_b32_e32 v225, 0, v115, vcc
	v_ashrrev_i32_e32 v115, 31, v171
	v_bitop3_b32 v115, v115, v171, s58 bitop3:0x36
	v_cmp_lt_i32_e32 vcc, s0, v240
	s_movk_i32 s0, 0x400
	ds_read2st64_b32 v[166:167], v16 offset0:18 offset1:19
	ds_read2st64_b32 v[168:169], v16 offset0:20 offset1:21
	ds_read2st64_b32 v[170:171], v16 offset0:22 offset1:23
	v_cndmask_b32_e32 v223, 0, v115, vcc
	s_waitcnt lgkmcnt(3)
	v_ashrrev_i32_e32 v115, 31, v164
	v_bitop3_b32 v115, v115, v164, s58 bitop3:0x36
	v_cmp_lt_i32_e32 vcc, s0, v240
	s_movk_i32 s0, 0x440
	v_cmp_lt_i32_e64 s[10:11], s10, v240
	v_cndmask_b32_e32 v224, 0, v115, vcc
	v_ashrrev_i32_e32 v115, 31, v165
	v_bitop3_b32 v115, v115, v165, s58 bitop3:0x36
	v_cmp_lt_i32_e32 vcc, s0, v240
	s_movk_i32 s0, 0x480
	ds_read2st64_b32 v[164:165], v16 offset0:24 offset1:25
	v_cndmask_b32_e32 v222, 0, v115, vcc
	s_waitcnt lgkmcnt(3)
	v_ashrrev_i32_e32 v115, 31, v166
	v_bitop3_b32 v115, v115, v166, s58 bitop3:0x36
	v_cmp_lt_i32_e32 vcc, s0, v240
	s_movk_i32 s0, 0x4c0
	s_cmp_lt_i32 s61, 4
	v_cndmask_b32_e32 v221, 0, v115, vcc
	v_ashrrev_i32_e32 v115, 31, v167
	v_bitop3_b32 v115, v115, v167, s58 bitop3:0x36
	v_cmp_lt_i32_e32 vcc, s0, v240
	s_movk_i32 s0, 0x500
	s_mov_b64 s[40:41], 0
	v_cndmask_b32_e32 v220, 0, v115, vcc
	s_waitcnt lgkmcnt(2)
	v_ashrrev_i32_e32 v115, 31, v168
	v_bitop3_b32 v115, v115, v168, s58 bitop3:0x36
	v_cmp_lt_i32_e32 vcc, s0, v240
	s_movk_i32 s0, 0x540
	s_nop 0
	v_cndmask_b32_e32 v219, 0, v115, vcc
	v_ashrrev_i32_e32 v115, 31, v169
	v_bitop3_b32 v115, v115, v169, s58 bitop3:0x36
	v_cmp_lt_i32_e32 vcc, s0, v240
	s_movk_i32 s0, 0x580
	s_nop 0
	v_cndmask_b32_e32 v218, 0, v115, vcc
	s_waitcnt lgkmcnt(1)
	v_ashrrev_i32_e32 v115, 31, v170
	v_bitop3_b32 v115, v115, v170, s58 bitop3:0x36
	v_cmp_lt_i32_e32 vcc, s0, v240
	s_movk_i32 s0, 0x5c0
	s_nop 0
	v_cndmask_b32_e32 v217, 0, v115, vcc
	v_ashrrev_i32_e32 v115, 31, v171
	v_bitop3_b32 v115, v115, v171, s58 bitop3:0x36
	v_cmp_lt_i32_e32 vcc, s0, v240
	s_movk_i32 s0, 0x600
	ds_read2st64_b32 v[166:167], v16 offset0:26 offset1:27
	ds_read2st64_b32 v[168:169], v16 offset0:28 offset1:29
	ds_read2st64_b32 v[170:171], v16 offset0:30 offset1:31
	v_cndmask_b32_e32 v215, 0, v115, vcc
	s_waitcnt lgkmcnt(3)
	v_ashrrev_i32_e32 v115, 31, v164
	v_bitop3_b32 v115, v115, v164, s58 bitop3:0x36
	v_cmp_lt_i32_e32 vcc, s0, v240
	s_movk_i32 s0, 0x640
	s_nop 0
	v_cndmask_b32_e32 v216, 0, v115, vcc
	v_ashrrev_i32_e32 v115, 31, v165
	v_bitop3_b32 v115, v115, v165, s58 bitop3:0x36
	v_cmp_lt_i32_e32 vcc, s0, v240
	s_movk_i32 s0, 0x680
	ds_read2st64_b32 v[164:165], v16 offset0:32 offset1:33
	v_cndmask_b32_e32 v214, 0, v115, vcc
	s_waitcnt lgkmcnt(3)
; __device__ __forceinline__ void select_group(unsigned char* ws, int r0, const bf16_t* __restrict__ kib, int n, float* sc, SelPre& pre, int nr0, const bf16_t* __restrict__ nkib, int nn) {
;     ...
;     unsigned x[64];
; #pragma unroll
;     for (int i = 0; i < 64; ++i) {
;       const unsigned ub = __float_as_uint(rowl[i * 64]);
;       const unsigned o = ub ^ ((unsigned)((int)ub >> 31) | 0x80000000u);
;       x[i] = (i * 64 < nl) ? o : 0u;
;     }
	v_ashrrev_i32_e32 v115, 31, v166
	v_bitop3_b32 v115, v115, v166, s58 bitop3:0x36
	v_cmp_lt_i32_e32 vcc, s0, v240
	s_movk_i32 s0, 0x6c0
	s_nop 0
	v_cndmask_b32_e32 v213, 0, v115, vcc
	v_ashrrev_i32_e32 v115, 31, v167
	v_bitop3_b32 v115, v115, v167, s58 bitop3:0x36
	v_cmp_lt_i32_e32 vcc, s0, v240
	s_movk_i32 s0, 0x700
	s_nop 0
	v_cndmask_b32_e32 v212, 0, v115, vcc
	s_waitcnt lgkmcnt(2)
	v_ashrrev_i32_e32 v115, 31, v168
	v_bitop3_b32 v115, v115, v168, s58 bitop3:0x36
	v_cmp_lt_i32_e32 vcc, s0, v240
	s_movk_i32 s0, 0x740
	s_nop 0
	v_cndmask_b32_e32 v211, 0, v115, vcc
	v_ashrrev_i32_e32 v115, 31, v169
	v_bitop3_b32 v115, v115, v169, s58 bitop3:0x36
	v_cmp_lt_i32_e32 vcc, s0, v240
	s_movk_i32 s0, 0x780
	s_nop 0
	v_cndmask_b32_e32 v210, 0, v115, vcc
	s_waitcnt lgkmcnt(1)
	v_ashrrev_i32_e32 v115, 31, v170
	v_bitop3_b32 v115, v115, v170, s58 bitop3:0x36
	v_cmp_lt_i32_e32 vcc, s0, v240
	s_movk_i32 s0, 0x7c0
	s_nop 0
	v_cndmask_b32_e32 v207, 0, v115, vcc
	v_ashrrev_i32_e32 v115, 31, v171
	v_bitop3_b32 v115, v115, v171, s58 bitop3:0x36
	v_cmp_lt_i32_e32 vcc, s0, v240
	s_movk_i32 s0, 0x800
	ds_read2st64_b32 v[166:167], v16 offset0:34 offset1:35
	ds_read2st64_b32 v[168:169], v16 offset0:36 offset1:37
	ds_read2st64_b32 v[170:171], v16 offset0:38 offset1:39
	v_cndmask_b32_e32 v194, 0, v115, vcc
	s_waitcnt lgkmcnt(3)
	v_ashrrev_i32_e32 v115, 31, v164
	v_bitop3_b32 v115, v115, v164, s58 bitop3:0x36
	v_cmp_lt_i32_e32 vcc, s0, v240
	s_movk_i32 s0, 0x840
	s_nop 0
	v_cndmask_b32_e32 v195, 0, v115, vcc
	v_ashrrev_i32_e32 v115, 31, v165
	v_bitop3_b32 v115, v115, v165, s58 bitop3:0x36
	v_cmp_lt_i32_e32 vcc, s0, v240
	s_movk_i32 s0, 0x880
	ds_read2st64_b32 v[164:165], v16 offset0:40 offset1:41
	v_cndmask_b32_e32 v193, 0, v115, vcc
	s_waitcnt lgkmcnt(3)
	v_ashrrev_i32_e32 v115, 31, v166
	v_bitop3_b32 v115, v115, v166, s58 bitop3:0x36
	v_cmp_lt_i32_e32 vcc, s0, v240
	s_movk_i32 s0, 0x8c0
	s_nop 0
	v_cndmask_b32_e32 v192, 0, v115, vcc
	v_ashrrev_i32_e32 v115, 31, v167
	v_bitop3_b32 v115, v115, v167, s58 bitop3:0x36
	v_cmp_lt_i32_e32 vcc, s0, v240
	s_movk_i32 s0, 0x900
	s_nop 0
	v_cndmask_b32_e32 v191, 0, v115, vcc
	s_waitcnt lgkmcnt(2)
	v_ashrrev_i32_e32 v115, 31, v168
	v_bitop3_b32 v115, v115, v168, s58 bitop3:0x36
	v_cmp_lt_i32_e32 vcc, s0, v240
	s_movk_i32 s0, 0x940
	s_nop 0
	v_cndmask_b32_e32 v190, 0, v115, vcc
	v_ashrrev_i32_e32 v115, 31, v169
	v_bitop3_b32 v115, v115, v169, s58 bitop3:0x36
	v_cmp_lt_i32_e32 vcc, s0, v240
	s_movk_i32 s0, 0x980
	s_nop 0
	v_cndmask_b32_e32 v189, 0, v115, vcc
	s_waitcnt lgkmcnt(1)
	v_ashrrev_i32_e32 v115, 31, v170
	v_bitop3_b32 v115, v115, v170, s58 bitop3:0x36
	v_cmp_lt_i32_e32 vcc, s0, v240
	s_movk_i32 s0, 0x9c0
	s_nop 0
	v_cndmask_b32_e32 v188, 0, v115, vcc
	v_ashrrev_i32_e32 v115, 31, v171
	v_bitop3_b32 v115, v115, v171, s58 bitop3:0x36
	v_cmp_lt_i32_e32 vcc, s0, v240
	s_movk_i32 s0, 0xa00
	ds_read2st64_b32 v[166:167], v16 offset0:42 offset1:43
	ds_read2st64_b32 v[168:169], v16 offset0:44 offset1:45
	ds_read2st64_b32 v[170:171], v16 offset0:46 offset1:47
	v_cndmask_b32_e32 v186, 0, v115, vcc
	s_waitcnt lgkmcnt(3)
	v_ashrrev_i32_e32 v115, 31, v164
	v_bitop3_b32 v115, v115, v164, s58 bitop3:0x36
	v_cmp_lt_i32_e32 vcc, s0, v240
	s_movk_i32 s0, 0xa40
	s_nop 0
	v_cndmask_b32_e32 v187, 0, v115, vcc
	v_ashrrev_i32_e32 v115, 31, v165
	v_bitop3_b32 v115, v115, v165, s58 bitop3:0x36
	v_cmp_lt_i32_e32 vcc, s0, v240
	s_movk_i32 s0, 0xa80
	ds_read2st64_b32 v[164:165], v16 offset0:48 offset1:49
	v_cndmask_b32_e32 v185, 0, v115, vcc
	s_waitcnt lgkmcnt(3)
	v_ashrrev_i32_e32 v115, 31, v166
	v_bitop3_b32 v115, v115, v166, s58 bitop3:0x36
	v_cmp_lt_i32_e32 vcc, s0, v240
	s_movk_i32 s0, 0xac0
	s_nop 0
	v_cndmask_b32_e32 v184, 0, v115, vcc
	v_ashrrev_i32_e32 v115, 31, v167
	v_bitop3_b32 v115, v115, v167, s58 bitop3:0x36
	v_cmp_lt_i32_e32 vcc, s0, v240
	s_movk_i32 s0, 0xb00
	s_nop 0
	v_cndmask_b32_e32 v183, 0, v115, vcc
	s_waitcnt lgkmcnt(2)
	v_ashrrev_i32_e32 v115, 31, v168
	v_bitop3_b32 v115, v115, v168, s58 bitop3:0x36
	v_cmp_lt_i32_e32 vcc, s0, v240
	s_movk_i32 s0, 0xb40
	s_nop 0
	v_cndmask_b32_e32 v182, 0, v115, vcc
	v_ashrrev_i32_e32 v115, 31, v169
	v_bitop3_b32 v115, v115, v169, s58 bitop3:0x36
	v_cmp_lt_i32_e32 vcc, s0, v240
	s_movk_i32 s0, 0xb80
	s_nop 0
	v_cndmask_b32_e32 v181, 0, v115, vcc
	s_waitcnt lgkmcnt(1)
	v_ashrrev_i32_e32 v115, 31, v170
	v_bitop3_b32 v115, v115, v170, s58 bitop3:0x36
	v_cmp_lt_i32_e32 vcc, s0, v240
	s_movk_i32 s0, 0xbc0
	s_nop 0
	v_cndmask_b32_e32 v180, 0, v115, vcc
	v_ashrrev_i32_e32 v115, 31, v171
	v_bitop3_b32 v115, v115, v171, s58 bitop3:0x36
	v_cmp_lt_i32_e32 vcc, s0, v240
	s_movk_i32 s0, 0xc00
	ds_read2st64_b32 v[166:167], v16 offset0:50 offset1:51
	ds_read2st64_b32 v[168:169], v16 offset0:52 offset1:53
	ds_read2st64_b32 v[170:171], v16 offset0:54 offset1:55
	v_cndmask_b32_e32 v178, 0, v115, vcc
	s_waitcnt lgkmcnt(3)
	v_ashrrev_i32_e32 v115, 31, v164
	v_bitop3_b32 v115, v115, v164, s58 bitop3:0x36
	v_cmp_lt_i32_e32 vcc, s0, v240
	s_movk_i32 s0, 0xc40
	s_nop 0
	v_cndmask_b32_e32 v179, 0, v115, vcc
	v_ashrrev_i32_e32 v115, 31, v165
	v_bitop3_b32 v115, v115, v165, s58 bitop3:0x36
	v_cmp_lt_i32_e32 vcc, s0, v240
	s_movk_i32 s0, 0xc80
	s_nop 0
	v_cndmask_b32_e32 v177, 0, v115, vcc
	s_waitcnt lgkmcnt(2)
	v_ashrrev_i32_e32 v115, 31, v166
	v_bitop3_b32 v115, v115, v166, s58 bitop3:0x36
	v_cmp_lt_i32_e32 vcc, s0, v240
	s_movk_i32 s0, 0xcc0
	s_nop 0
	v_cndmask_b32_e32 v176, 0, v115, vcc
	v_ashrrev_i32_e32 v115, 31, v167
	v_bitop3_b32 v115, v115, v167, s58 bitop3:0x36
	v_cmp_lt_i32_e32 vcc, s0, v240
	s_movk_i32 s0, 0xd00
	s_nop 0
	v_cndmask_b32_e32 v175, 0, v115, vcc
	s_waitcnt lgkmcnt(1)
	v_ashrrev_i32_e32 v115, 31, v168
	v_bitop3_b32 v115, v115, v168, s58 bitop3:0x36
	v_cmp_lt_i32_e32 vcc, s0, v240
	s_movk_i32 s0, 0xd40
	s_nop 0
	v_cndmask_b32_e32 v174, 0, v115, vcc
	v_ashrrev_i32_e32 v115, 31, v169
	v_bitop3_b32 v115, v115, v169, s58 bitop3:0x36
	v_cmp_lt_i32_e32 vcc, s0, v240
	s_movk_i32 s0, 0xd80
	s_nop 0
	v_cndmask_b32_e32 v173, 0, v115, vcc
	s_waitcnt lgkmcnt(0)
	v_ashrrev_i32_e32 v115, 31, v170
	v_bitop3_b32 v115, v115, v170, s58 bitop3:0x36
	v_cmp_lt_i32_e32 vcc, s0, v240
	s_movk_i32 s0, 0xdc0
	s_nop 0
	v_cndmask_b32_e32 v172, 0, v115, vcc
	v_ashrrev_i32_e32 v115, 31, v171
	v_bitop3_b32 v115, v115, v171, s58 bitop3:0x36
	v_cmp_lt_i32_e32 vcc, s0, v240
	s_movk_i32 s0, 0xe00
	ds_read2st64_b32 v[170:171], v16 offset0:56 offset1:57
	ds_read2st64_b32 v[168:169], v16 offset0:58 offset1:59
	ds_read2st64_b32 v[166:167], v16 offset0:60 offset1:61
	ds_read2st64_b32 v[164:165], v16 offset0:62 offset1:63
	v_cmp_lt_i32_e64 s[12:13], s0, v240
	s_movk_i32 s0, 0xe40
	v_cmp_lt_i32_e64 s[6:7], s0, v240
	s_movk_i32 s0, 0xe80
	v_cmp_lt_i32_e64 s[8:9], s0, v240
	s_movk_i32 s0, 0xec0
	v_cmp_lt_i32_e64 s[2:3], s0, v240
	s_movk_i32 s0, 0xf00
	v_cmp_lt_i32_e64 s[4:5], s0, v240
	s_movk_i32 s0, 0xf40
	v_cndmask_b32_e32 v115, 0, v115, vcc
	v_cmp_lt_i32_e64 s[0:1], s0, v240
	s_cbranch_scc1 .LBB0_2941
; template <int NB>
; __device__ __forceinline__ void bisect256(const unsigned (&x)[64], unsigned& tau_out, int& cge_out) {
;   unsigned tau = 0u;
;   int cge = 0;
;     ...
;     const unsigned cand = tau | (1u << bit);
; __device__ __forceinline__ void select_group(unsigned char* ws, int r0, const bf16_t* __restrict__ kib, int n, float* sc, SelPre& pre, int nr0, const bf16_t* __restrict__ nkib, int nn) {
;     ...
;     switch ((nreg + 7) >> 3) {
;       case 1: bisect256<1>(x, tau, cge); break;
;       case 2: bisect256<2>(x, tau, cge); break;
;       case 3: bisect256<3>(x, tau, cge); break;
;       case 4: bisect256<4>(x, tau, cge); break;
;       case 5: bisect256<5>(x, tau, cge); break;
;       case 6: bisect256<6>(x, tau, cge); break;
;       case 7: bisect256<7>(x, tau, cge); break;
;       default: bisect256<8>(x, tau, cge); break;
;     }
	s_cmp_gt_i32 s61, 5
	s_cbranch_scc0 .LBB0_2942
	s_cmp_gt_i32 s61, 6
	s_cbranch_scc0 .LBB0_2943
	s_cmp_eq_u32 s61, 7
	s_cbranch_scc0 .LBB0_2944
	s_mov_b32 s59, 0
	v_max_u32_e32 v240, v239, v238
	v_max3_u32 v240, v240, v237, v236
	v_max3_u32 v240, v240, v235, v234
	v_max3_u32 v240, v240, v233, v231
	v_max3_u32 v240, v240, v232, v230
	v_max3_u32 v240, v240, v229, v228
	v_max3_u32 v240, v240, v227, v226
	v_max3_u32 v240, v240, v225, v223
	v_max3_u32 v240, v240, v224, v222
	v_max3_u32 v240, v240, v221, v220
	v_max3_u32 v240, v240, v219, v218
	v_max3_u32 v240, v240, v217, v215
	v_max3_u32 v240, v240, v216, v214
	v_max3_u32 v240, v240, v213, v212
	v_max3_u32 v240, v240, v211, v210
	v_max3_u32 v240, v240, v207, v194
	v_max3_u32 v240, v240, v195, v193
	v_max3_u32 v240, v240, v192, v191
	v_max3_u32 v240, v240, v190, v189
	v_max3_u32 v240, v240, v188, v186
	v_max3_u32 v240, v240, v187, v185
	v_max3_u32 v240, v240, v184, v183
	v_max3_u32 v240, v240, v182, v181
	v_max3_u32 v240, v240, v180, v178
	v_max3_u32 v240, v240, v179, v177
	v_max3_u32 v240, v240, v176, v175
	v_max3_u32 v240, v240, v174, v173
	v_max3_u32 v240, v240, v172, v115
	s_nop 1
	v_max_u32_dpp v240, v240, v240 row_shr:1 row_mask:0xf bank_mask:0xf bound_ctrl:1
	s_nop 1
	v_max_u32_dpp v240, v240, v240 row_shr:2 row_mask:0xf bank_mask:0xf bound_ctrl:1
	s_nop 1
	v_max_u32_dpp v240, v240, v240 row_shr:4 row_mask:0xf bank_mask:0xf bound_ctrl:1
	s_nop 1
	v_max_u32_dpp v240, v240, v240 row_shr:8 row_mask:0xf bank_mask:0xf bound_ctrl:1
	s_nop 0
	v_readlane_b32 s38, v240, 15
	v_readlane_b32 s39, v240, 31
	s_max_u32 s38, s38, s39
	v_readlane_b32 s39, v240, 47
	s_max_u32 s38, s38, s39
	v_readlane_b32 s39, v240, 63
	s_max_u32 s38, s38, s39
	s_add_u32 s100, s38, 1
	s_cselect_b32 s100, -1, s100
	s_mov_b32 s101, 0
	s_mov_b32 s43, 0x1000000
	v_writelane_b32 v255, s43, 48
	v_writelane_b32 v255, s100, 49
	s_nop 1
.Lsel0_top:
	v_readlane_b32 s43, v255, 48
	s_cmp_eq_u32 s43, 0
	s_cbranch_scc1 .Lsel0_mid
	v_readlane_b32 s62, v255, 49
	s_lshl_b32 s63, s43, 3
	s_cmp_ge_u32 s43, 0x40000000
	s_cselect_b32 s63, 0, s63
	v_writelane_b32 v255, s63, 48
	s_sub_u32 s42, s62, s43
	s_cbranch_scc1 .Lsel0_goff
	s_cmp_gt_u32 s42, s101
	s_cbranch_scc1 .Lsel0_count
.Lsel0_goff:
	s_mov_b32 s63, 0
	v_writelane_b32 v255, s63, 48
.Lsel0_mid:
	s_sub_u32 s42, s100, s101
	s_lshr_b32 s42, s42, 1
	s_add_u32 s42, s42, s101
; template <int NB>
; __device__ __forceinline__ void bisect256(const unsigned (&x)[64], unsigned& tau_out, int& cge_out) {
;     ...
;     unsigned cl = 0u;
; #pragma unroll
;     for (int blk = 0; blk < NB; ++blk) {
;       unsigned long long m0, m1, m2, m3, m4, m5, m6, m7;
;       asm volatile(
;           "v_cmp_ge_u32_e64 %1, %9, %17\n\tv_cmp_ge_u32_e64 %2, %10, %17\n\tv_cmp_ge_u32_e64 %3, %11, %17\n\tv_cmp_ge_u32_e64 %4, %12, %17\n\t"
;           "v_cmp_ge_u32_e64 %5, %13, %17\n\tv_cmp_ge_u32_e64 %6, %14, %17\n\tv_cmp_ge_u32_e64 %7, %15, %17\n\tv_cmp_ge_u32_e64 %8, %16, %17\n\t"
;           "v_addc_co_u32_e64 %0, %1, 0, %0, %1\n\tv_addc_co_u32_e64 %0, %2, 0, %0, %2\n\tv_addc_co_u32_e64 %0, %3, 0, %0, %3\n\t"
;           "v_addc_co_u32_e64 %0, %4, 0, %0, %4\n\tv_addc_co_u32_e64 %0, %5, 0, %0, %5\n\tv_addc_co_u32_e64 %0, %6, 0, %0, %6\n\t"
;           "v_addc_co_u32_e64 %0, %7, 0, %0, %7\n\tv_addc_co_u32_e64 %0, %8, 0, %0, %8"
;           : "+v"(cl), "=&s"(m0), "=&s"(m1), "=&s"(m2), "=&s"(m3), "=&s"(m4), "=&s"(m5), "=&s"(m6), "=&s"(m7)
;           : "v"(x[blk * 8 + 0]), "v"(x[blk * 8 + 1]), "v"(x[blk * 8 + 2]), "v"(x[blk * 8 + 3]), "v"(x[blk * 8 + 4]), "v"(x[blk * 8 + 5]),
;             "v"(x[blk * 8 + 6]), "v"(x[blk * 8 + 7]), "v"(cand));
;     }
;     cl += (unsigned)__builtin_amdgcn_update_dpp(0, (int)cl, 0x111, 0xf, 0xf, true);
;     cl += (unsigned)__builtin_amdgcn_update_dpp(0, (int)cl, 0x112, 0xf, 0xf, true);
;     cl += (unsigned)__builtin_amdgcn_update_dpp(0, (int)cl, 0x114, 0xf, 0xf, true);
;     cl += (unsigned)__builtin_amdgcn_update_dpp(0, (int)cl, 0x118, 0xf, 0xf, true);
;     const int cnt = __builtin_amdgcn_readlane((int)cl, 15) + __builtin_amdgcn_readlane((int)cl, 31) + __builtin_amdgcn_readlane((int)cl, 47) +
;                     __builtin_amdgcn_readlane((int)cl, 63);
;     if (cnt >= 256) { tau = cand; cge = cnt; }
;     if (cnt == 256) break;
;   }
.Lsel0_count:
	v_mov_b32_e32 v241, s42
	v_mov_b32_e32 v242, v17
	v_cmp_ge_u32_e64 s[38:39], v239, v241
	v_cmp_ge_u32_e64 s[42:43], v238, v241
	v_cmp_ge_u32_e64 s[62:63], v237, v241
	v_cmp_ge_u32_e64 s[64:65], v236, v241
	v_cmp_ge_u32_e64 s[66:67], v235, v241
	v_cmp_ge_u32_e64 s[68:69], v234, v241
	v_cmp_ge_u32_e64 s[70:71], v233, v241
	v_cmp_ge_u32_e64 s[72:73], v231, v241
	v_addc_co_u32_e64 v242, s[38:39], 0, v242, s[38:39]
	v_addc_co_u32_e64 v242, s[42:43], 0, v242, s[42:43]
	v_addc_co_u32_e64 v242, s[62:63], 0, v242, s[62:63]
	v_addc_co_u32_e64 v242, s[64:65], 0, v242, s[64:65]
	v_addc_co_u32_e64 v242, s[66:67], 0, v242, s[66:67]
	v_addc_co_u32_e64 v242, s[68:69], 0, v242, s[68:69]
	v_addc_co_u32_e64 v242, s[70:71], 0, v242, s[70:71]
	v_addc_co_u32_e64 v242, s[72:73], 0, v242, s[72:73]
	s_nop 0
	v_cmp_ge_u32_e64 s[38:39], v232, v241
	v_cmp_ge_u32_e64 s[42:43], v230, v241
	v_cmp_ge_u32_e64 s[62:63], v229, v241
	v_cmp_ge_u32_e64 s[64:65], v228, v241
	v_cmp_ge_u32_e64 s[66:67], v227, v241
	v_cmp_ge_u32_e64 s[68:69], v226, v241
	v_cmp_ge_u32_e64 s[70:71], v225, v241
	v_cmp_ge_u32_e64 s[72:73], v223, v241
	v_addc_co_u32_e64 v242, s[38:39], 0, v242, s[38:39]
	v_addc_co_u32_e64 v242, s[42:43], 0, v242, s[42:43]
	v_addc_co_u32_e64 v242, s[62:63], 0, v242, s[62:63]
	v_addc_co_u32_e64 v242, s[64:65], 0, v242, s[64:65]
	v_addc_co_u32_e64 v242, s[66:67], 0, v242, s[66:67]
	v_addc_co_u32_e64 v242, s[68:69], 0, v242, s[68:69]
	v_addc_co_u32_e64 v242, s[70:71], 0, v242, s[70:71]
	v_addc_co_u32_e64 v242, s[72:73], 0, v242, s[72:73]
	s_nop 0
	v_cmp_ge_u32_e64 s[38:39], v224, v241
	v_cmp_ge_u32_e64 s[42:43], v222, v241
	v_cmp_ge_u32_e64 s[62:63], v221, v241
	v_cmp_ge_u32_e64 s[64:65], v220, v241
	v_cmp_ge_u32_e64 s[66:67], v219, v241
	v_cmp_ge_u32_e64 s[68:69], v218, v241
	v_cmp_ge_u32_e64 s[70:71], v217, v241
	v_cmp_ge_u32_e64 s[72:73], v215, v241
	v_addc_co_u32_e64 v242, s[38:39], 0, v242, s[38:39]
	v_addc_co_u32_e64 v242, s[42:43], 0, v242, s[42:43]
	v_addc_co_u32_e64 v242, s[62:63], 0, v242, s[62:63]
	v_addc_co_u32_e64 v242, s[64:65], 0, v242, s[64:65]
	v_addc_co_u32_e64 v242, s[66:67], 0, v242, s[66:67]
	v_addc_co_u32_e64 v242, s[68:69], 0, v242, s[68:69]
	v_addc_co_u32_e64 v242, s[70:71], 0, v242, s[70:71]
	v_addc_co_u32_e64 v242, s[72:73], 0, v242, s[72:73]
	s_nop 0
	v_cmp_ge_u32_e64 s[38:39], v216, v241
	v_cmp_ge_u32_e64 s[42:43], v214, v241
	v_cmp_ge_u32_e64 s[62:63], v213, v241
	v_cmp_ge_u32_e64 s[64:65], v212, v241
	v_cmp_ge_u32_e64 s[66:67], v211, v241
	v_cmp_ge_u32_e64 s[68:69], v210, v241
	v_cmp_ge_u32_e64 s[70:71], v207, v241
	v_cmp_ge_u32_e64 s[72:73], v194, v241
	v_addc_co_u32_e64 v242, s[38:39], 0, v242, s[38:39]
	v_addc_co_u32_e64 v242, s[42:43], 0, v242, s[42:43]
	v_addc_co_u32_e64 v242, s[62:63], 0, v242, s[62:63]
	v_addc_co_u32_e64 v242, s[64:65], 0, v242, s[64:65]
	v_addc_co_u32_e64 v242, s[66:67], 0, v242, s[66:67]
	v_addc_co_u32_e64 v242, s[68:69], 0, v242, s[68:69]
	v_addc_co_u32_e64 v242, s[70:71], 0, v242, s[70:71]
	v_addc_co_u32_e64 v242, s[72:73], 0, v242, s[72:73]
	s_nop 0
	v_cmp_ge_u32_e64 s[38:39], v195, v241
	v_cmp_ge_u32_e64 s[42:43], v193, v241
	v_cmp_ge_u32_e64 s[62:63], v192, v241
	v_cmp_ge_u32_e64 s[64:65], v191, v241
	v_cmp_ge_u32_e64 s[66:67], v190, v241
	v_cmp_ge_u32_e64 s[68:69], v189, v241
	v_cmp_ge_u32_e64 s[70:71], v188, v241
	v_cmp_ge_u32_e64 s[72:73], v186, v241
	v_addc_co_u32_e64 v242, s[38:39], 0, v242, s[38:39]
	v_addc_co_u32_e64 v242, s[42:43], 0, v242, s[42:43]
	v_addc_co_u32_e64 v242, s[62:63], 0, v242, s[62:63]
	v_addc_co_u32_e64 v242, s[64:65], 0, v242, s[64:65]
	v_addc_co_u32_e64 v242, s[66:67], 0, v242, s[66:67]
	v_addc_co_u32_e64 v242, s[68:69], 0, v242, s[68:69]
	v_addc_co_u32_e64 v242, s[70:71], 0, v242, s[70:71]
	v_addc_co_u32_e64 v242, s[72:73], 0, v242, s[72:73]
	s_nop 0
	v_cmp_ge_u32_e64 s[38:39], v187, v241
	v_cmp_ge_u32_e64 s[42:43], v185, v241
	v_cmp_ge_u32_e64 s[62:63], v184, v241
	v_cmp_ge_u32_e64 s[64:65], v183, v241
	v_cmp_ge_u32_e64 s[66:67], v182, v241
	v_cmp_ge_u32_e64 s[68:69], v181, v241
	v_cmp_ge_u32_e64 s[70:71], v180, v241
	v_cmp_ge_u32_e64 s[72:73], v178, v241
	v_addc_co_u32_e64 v242, s[38:39], 0, v242, s[38:39]
	v_addc_co_u32_e64 v242, s[42:43], 0, v242, s[42:43]
	v_addc_co_u32_e64 v242, s[62:63], 0, v242, s[62:63]
	v_addc_co_u32_e64 v242, s[64:65], 0, v242, s[64:65]
	v_addc_co_u32_e64 v242, s[66:67], 0, v242, s[66:67]
	v_addc_co_u32_e64 v242, s[68:69], 0, v242, s[68:69]
	v_addc_co_u32_e64 v242, s[70:71], 0, v242, s[70:71]
	v_addc_co_u32_e64 v242, s[72:73], 0, v242, s[72:73]
	s_nop 0
	v_cmp_ge_u32_e64 s[38:39], v179, v241
	v_cmp_ge_u32_e64 s[42:43], v177, v241
	v_cmp_ge_u32_e64 s[62:63], v176, v241
	v_cmp_ge_u32_e64 s[64:65], v175, v241
	v_cmp_ge_u32_e64 s[66:67], v174, v241
	v_cmp_ge_u32_e64 s[68:69], v173, v241
	v_cmp_ge_u32_e64 s[70:71], v172, v241
	v_cmp_ge_u32_e64 s[72:73], v115, v241
	v_addc_co_u32_e64 v242, s[38:39], 0, v242, s[38:39]
	v_addc_co_u32_e64 v242, s[42:43], 0, v242, s[42:43]
	v_addc_co_u32_e64 v242, s[62:63], 0, v242, s[62:63]
	v_addc_co_u32_e64 v242, s[64:65], 0, v242, s[64:65]
	v_addc_co_u32_e64 v242, s[66:67], 0, v242, s[66:67]
	v_addc_co_u32_e64 v242, s[68:69], 0, v242, s[68:69]
	v_addc_co_u32_e64 v242, s[70:71], 0, v242, s[70:71]
	v_addc_co_u32_e64 v242, s[72:73], 0, v242, s[72:73]
	s_nop 1
	v_add_u32_dpp v242, v242, v242 row_shr:1 row_mask:0xf bank_mask:0xf bound_ctrl:1
	s_nop 1
	v_add_u32_dpp v242, v242, v242 row_shr:2 row_mask:0xf bank_mask:0xf bound_ctrl:1
	s_nop 1
	v_add_u32_dpp v242, v242, v242 row_shr:4 row_mask:0xf bank_mask:0xf bound_ctrl:1
	s_nop 1
	v_add_u32_dpp v242, v242, v242 row_shr:8 row_mask:0xf bank_mask:0xf bound_ctrl:1
	s_nop 0
	v_readlane_b32 s38, v242, 15
	v_readlane_b32 s39, v242, 31
	s_add_i32 s38, s39, s38
	v_readlane_b32 s39, v242, 47
	s_add_i32 s38, s38, s39
	v_readlane_b32 s39, v242, 63
	s_add_i32 s38, s38, s39
	v_readfirstlane_b32 s42, v241
	s_cmpk_gt_i32 s38, 0xff
	s_cbranch_scc0 .Lsel0_fail
	s_mov_b32 s101, s42
	s_mov_b32 s59, s38
	s_mov_b32 s63, 0
	v_writelane_b32 v255, s63, 48
	s_cmpk_eq_i32 s38, 0x100
	s_cbranch_scc1 .Lsel0_exit
	s_branch .Lsel0_chk
.Lsel0_fail:
	s_mov_b32 s100, s42
.Lsel0_chk:
	s_sub_u32 s64, s100, s101
	s_cmp_le_u32 s64, 1
	s_cbranch_scc0 .Lsel0_top
.Lsel0_exit:
	v_mov_b32_e32 v16, s101
	s_mov_b64 s[38:39], 0
	s_branch .LBB0_2947

; template <int NB>
; __device__ __forceinline__ void bisect256(const unsigned (&x)[64], unsigned& tau_out, int& cge_out) {
;   unsigned tau = 0u;
;   int cge = 0;
;     ...
;     const unsigned cand = tau | (1u << bit);
; __device__ __forceinline__ void select_group(unsigned char* ws, int r0, const bf16_t* __restrict__ kib, int n, float* sc, SelPre& pre, int nr0, const bf16_t* __restrict__ nkib, int nn) {
;     ...
;     switch ((nreg + 7) >> 3) {
;       case 1: bisect256<1>(x, tau, cge); break;
;       case 2: bisect256<2>(x, tau, cge); break;
;       case 3: bisect256<3>(x, tau, cge); break;
;       case 4: bisect256<4>(x, tau, cge); break;
;       case 5: bisect256<5>(x, tau, cge); break;
;       case 6: bisect256<6>(x, tau, cge); break;
;       case 7: bisect256<7>(x, tau, cge); break;
;       default: bisect256<8>(x, tau, cge); break;
;     }
.LBB0_2945:
	s_mov_b32 s59, 0
	v_max_u32_e32 v240, v239, v238
	v_max3_u32 v240, v240, v237, v236
	v_max3_u32 v240, v240, v235, v234
	v_max3_u32 v240, v240, v233, v231
	v_max3_u32 v240, v240, v232, v230
	v_max3_u32 v240, v240, v229, v228
	v_max3_u32 v240, v240, v227, v226
	v_max3_u32 v240, v240, v225, v223
	v_max3_u32 v240, v240, v224, v222
	v_max3_u32 v240, v240, v221, v220
	v_max3_u32 v240, v240, v219, v218
	v_max3_u32 v240, v240, v217, v215
	v_max3_u32 v240, v240, v216, v214
	v_max3_u32 v240, v240, v213, v212
	v_max3_u32 v240, v240, v211, v210
	v_max3_u32 v240, v240, v207, v194
	v_max3_u32 v240, v240, v195, v193
	v_max3_u32 v240, v240, v192, v191
	v_max3_u32 v240, v240, v190, v189
	v_max3_u32 v240, v240, v188, v186
	v_max3_u32 v240, v240, v187, v185
	v_max3_u32 v240, v240, v184, v183
	v_max3_u32 v240, v240, v182, v181
	v_max3_u32 v240, v240, v180, v178
	s_nop 1
	v_max_u32_dpp v240, v240, v240 row_shr:1 row_mask:0xf bank_mask:0xf bound_ctrl:1
	s_nop 1
	v_max_u32_dpp v240, v240, v240 row_shr:2 row_mask:0xf bank_mask:0xf bound_ctrl:1
	s_nop 1
	v_max_u32_dpp v240, v240, v240 row_shr:4 row_mask:0xf bank_mask:0xf bound_ctrl:1
	s_nop 1
	v_max_u32_dpp v240, v240, v240 row_shr:8 row_mask:0xf bank_mask:0xf bound_ctrl:1
	s_nop 0
	v_readlane_b32 s42, v240, 15
	v_readlane_b32 s43, v240, 31
	s_max_u32 s42, s42, s43
	v_readlane_b32 s43, v240, 47
	s_max_u32 s42, s42, s43
	v_readlane_b32 s43, v240, 63
	s_max_u32 s42, s42, s43
	s_add_u32 s100, s42, 1
	s_cselect_b32 s100, -1, s100
	s_mov_b32 s101, 0
	s_mov_b32 s63, 0x1000000
	v_writelane_b32 v255, s63, 48
	v_writelane_b32 v255, s100, 49
	s_nop 1
.Lsel1_top:
	v_readlane_b32 s63, v255, 48
	s_cmp_eq_u32 s63, 0
	s_cbranch_scc1 .Lsel1_mid
	v_readlane_b32 s64, v255, 49
	s_lshl_b32 s65, s63, 3
	s_cmp_ge_u32 s63, 0x40000000
	s_cselect_b32 s65, 0, s65
	v_writelane_b32 v255, s65, 48
	s_sub_u32 s62, s64, s63
	s_cbranch_scc1 .Lsel1_goff
	s_cmp_gt_u32 s62, s101
	s_cbranch_scc1 .Lsel1_count
.Lsel1_goff:
	s_mov_b32 s65, 0
	v_writelane_b32 v255, s65, 48
.Lsel1_mid:
	s_sub_u32 s62, s100, s101
	s_lshr_b32 s62, s62, 1
	s_add_u32 s62, s62, s101
; template <int NB>
; __device__ __forceinline__ void bisect256(const unsigned (&x)[64], unsigned& tau_out, int& cge_out) {
;     ...
;     unsigned cl = 0u;
; #pragma unroll
;     for (int blk = 0; blk < NB; ++blk) {
;       unsigned long long m0, m1, m2, m3, m4, m5, m6, m7;
;       asm volatile(
;           "v_cmp_ge_u32_e64 %1, %9, %17\n\tv_cmp_ge_u32_e64 %2, %10, %17\n\tv_cmp_ge_u32_e64 %3, %11, %17\n\tv_cmp_ge_u32_e64 %4, %12, %17\n\t"
;           "v_cmp_ge_u32_e64 %5, %13, %17\n\tv_cmp_ge_u32_e64 %6, %14, %17\n\tv_cmp_ge_u32_e64 %7, %15, %17\n\tv_cmp_ge_u32_e64 %8, %16, %17\n\t"
;           "v_addc_co_u32_e64 %0, %1, 0, %0, %1\n\tv_addc_co_u32_e64 %0, %2, 0, %0, %2\n\tv_addc_co_u32_e64 %0, %3, 0, %0, %3\n\t"
;           "v_addc_co_u32_e64 %0, %4, 0, %0, %4\n\tv_addc_co_u32_e64 %0, %5, 0, %0, %5\n\tv_addc_co_u32_e64 %0, %6, 0, %0, %6\n\t"
;           "v_addc_co_u32_e64 %0, %7, 0, %0, %7\n\tv_addc_co_u32_e64 %0, %8, 0, %0, %8"
;           : "+v"(cl), "=&s"(m0), "=&s"(m1), "=&s"(m2), "=&s"(m3), "=&s"(m4), "=&s"(m5), "=&s"(m6), "=&s"(m7)
;           : "v"(x[blk * 8 + 0]), "v"(x[blk * 8 + 1]), "v"(x[blk * 8 + 2]), "v"(x[blk * 8 + 3]), "v"(x[blk * 8 + 4]), "v"(x[blk * 8 + 5]),
;             "v"(x[blk * 8 + 6]), "v"(x[blk * 8 + 7]), "v"(cand));
;     }
;     cl += (unsigned)__builtin_amdgcn_update_dpp(0, (int)cl, 0x111, 0xf, 0xf, true);
;     cl += (unsigned)__builtin_amdgcn_update_dpp(0, (int)cl, 0x112, 0xf, 0xf, true);
;     cl += (unsigned)__builtin_amdgcn_update_dpp(0, (int)cl, 0x114, 0xf, 0xf, true);
;     cl += (unsigned)__builtin_amdgcn_update_dpp(0, (int)cl, 0x118, 0xf, 0xf, true);
;     const int cnt = __builtin_amdgcn_readlane((int)cl, 15) + __builtin_amdgcn_readlane((int)cl, 31) + __builtin_amdgcn_readlane((int)cl, 47) +
;                     __builtin_amdgcn_readlane((int)cl, 63);
;     if (cnt >= 256) { tau = cand; cge = cnt; }
;     if (cnt == 256) break;
;   }
.Lsel1_count:
	v_mov_b32_e32 v241, s62
	v_mov_b32_e32 v242, v17
	v_cmp_ge_u32_e64 s[42:43], v239, v241
	v_cmp_ge_u32_e64 s[62:63], v238, v241
	v_cmp_ge_u32_e64 s[64:65], v237, v241
	v_cmp_ge_u32_e64 s[66:67], v236, v241
	v_cmp_ge_u32_e64 s[68:69], v235, v241
	v_cmp_ge_u32_e64 s[70:71], v234, v241
	v_cmp_ge_u32_e64 s[72:73], v233, v241
	v_cmp_ge_u32_e64 s[74:75], v231, v241
	v_addc_co_u32_e64 v242, s[42:43], 0, v242, s[42:43]
	v_addc_co_u32_e64 v242, s[62:63], 0, v242, s[62:63]
	v_addc_co_u32_e64 v242, s[64:65], 0, v242, s[64:65]
	v_addc_co_u32_e64 v242, s[66:67], 0, v242, s[66:67]
	v_addc_co_u32_e64 v242, s[68:69], 0, v242, s[68:69]
	v_addc_co_u32_e64 v242, s[70:71], 0, v242, s[70:71]
	v_addc_co_u32_e64 v242, s[72:73], 0, v242, s[72:73]
	v_addc_co_u32_e64 v242, s[74:75], 0, v242, s[74:75]
	s_nop 0
	v_cmp_ge_u32_e64 s[42:43], v232, v241
	v_cmp_ge_u32_e64 s[62:63], v230, v241
	v_cmp_ge_u32_e64 s[64:65], v229, v241
	v_cmp_ge_u32_e64 s[66:67], v228, v241
	v_cmp_ge_u32_e64 s[68:69], v227, v241
	v_cmp_ge_u32_e64 s[70:71], v226, v241
	v_cmp_ge_u32_e64 s[72:73], v225, v241
	v_cmp_ge_u32_e64 s[74:75], v223, v241
	v_addc_co_u32_e64 v242, s[42:43], 0, v242, s[42:43]
	v_addc_co_u32_e64 v242, s[62:63], 0, v242, s[62:63]
	v_addc_co_u32_e64 v242, s[64:65], 0, v242, s[64:65]
	v_addc_co_u32_e64 v242, s[66:67], 0, v242, s[66:67]
	v_addc_co_u32_e64 v242, s[68:69], 0, v242, s[68:69]
	v_addc_co_u32_e64 v242, s[70:71], 0, v242, s[70:71]
	v_addc_co_u32_e64 v242, s[72:73], 0, v242, s[72:73]
	v_addc_co_u32_e64 v242, s[74:75], 0, v242, s[74:75]
	s_nop 0
	v_cmp_ge_u32_e64 s[42:43], v224, v241
	v_cmp_ge_u32_e64 s[62:63], v222, v241
	v_cmp_ge_u32_e64 s[64:65], v221, v241
	v_cmp_ge_u32_e64 s[66:67], v220, v241
	v_cmp_ge_u32_e64 s[68:69], v219, v241
	v_cmp_ge_u32_e64 s[70:71], v218, v241
	v_cmp_ge_u32_e64 s[72:73], v217, v241
	v_cmp_ge_u32_e64 s[74:75], v215, v241
	v_addc_co_u32_e64 v242, s[42:43], 0, v242, s[42:43]
	v_addc_co_u32_e64 v242, s[62:63], 0, v242, s[62:63]
	v_addc_co_u32_e64 v242, s[64:65], 0, v242, s[64:65]
	v_addc_co_u32_e64 v242, s[66:67], 0, v242, s[66:67]
	v_addc_co_u32_e64 v242, s[68:69], 0, v242, s[68:69]
	v_addc_co_u32_e64 v242, s[70:71], 0, v242, s[70:71]
	v_addc_co_u32_e64 v242, s[72:73], 0, v242, s[72:73]
	v_addc_co_u32_e64 v242, s[74:75], 0, v242, s[74:75]
	s_nop 0
	v_cmp_ge_u32_e64 s[42:43], v216, v241
	v_cmp_ge_u32_e64 s[62:63], v214, v241
	v_cmp_ge_u32_e64 s[64:65], v213, v241
	v_cmp_ge_u32_e64 s[66:67], v212, v241
	v_cmp_ge_u32_e64 s[68:69], v211, v241
	v_cmp_ge_u32_e64 s[70:71], v210, v241
	v_cmp_ge_u32_e64 s[72:73], v207, v241
	v_cmp_ge_u32_e64 s[74:75], v194, v241
	v_addc_co_u32_e64 v242, s[42:43], 0, v242, s[42:43]
	v_addc_co_u32_e64 v242, s[62:63], 0, v242, s[62:63]
	v_addc_co_u32_e64 v242, s[64:65], 0, v242, s[64:65]
	v_addc_co_u32_e64 v242, s[66:67], 0, v242, s[66:67]
	v_addc_co_u32_e64 v242, s[68:69], 0, v242, s[68:69]
	v_addc_co_u32_e64 v242, s[70:71], 0, v242, s[70:71]
	v_addc_co_u32_e64 v242, s[72:73], 0, v242, s[72:73]
	v_addc_co_u32_e64 v242, s[74:75], 0, v242, s[74:75]
	s_nop 0
	v_cmp_ge_u32_e64 s[42:43], v195, v241
	v_cmp_ge_u32_e64 s[62:63], v193, v241
	v_cmp_ge_u32_e64 s[64:65], v192, v241
	v_cmp_ge_u32_e64 s[66:67], v191, v241
	v_cmp_ge_u32_e64 s[68:69], v190, v241
	v_cmp_ge_u32_e64 s[70:71], v189, v241
	v_cmp_ge_u32_e64 s[72:73], v188, v241
	v_cmp_ge_u32_e64 s[74:75], v186, v241
	v_addc_co_u32_e64 v242, s[42:43], 0, v242, s[42:43]
	v_addc_co_u32_e64 v242, s[62:63], 0, v242, s[62:63]
	v_addc_co_u32_e64 v242, s[64:65], 0, v242, s[64:65]
	v_addc_co_u32_e64 v242, s[66:67], 0, v242, s[66:67]
	v_addc_co_u32_e64 v242, s[68:69], 0, v242, s[68:69]
	v_addc_co_u32_e64 v242, s[70:71], 0, v242, s[70:71]
	v_addc_co_u32_e64 v242, s[72:73], 0, v242, s[72:73]
	v_addc_co_u32_e64 v242, s[74:75], 0, v242, s[74:75]
	s_nop 0
	v_cmp_ge_u32_e64 s[42:43], v187, v241
	v_cmp_ge_u32_e64 s[62:63], v185, v241
	v_cmp_ge_u32_e64 s[64:65], v184, v241
	v_cmp_ge_u32_e64 s[66:67], v183, v241
	v_cmp_ge_u32_e64 s[68:69], v182, v241
	v_cmp_ge_u32_e64 s[70:71], v181, v241
	v_cmp_ge_u32_e64 s[72:73], v180, v241
	v_cmp_ge_u32_e64 s[74:75], v178, v241
	v_addc_co_u32_e64 v242, s[42:43], 0, v242, s[42:43]
	v_addc_co_u32_e64 v242, s[62:63], 0, v242, s[62:63]
	v_addc_co_u32_e64 v242, s[64:65], 0, v242, s[64:65]
	v_addc_co_u32_e64 v242, s[66:67], 0, v242, s[66:67]
	v_addc_co_u32_e64 v242, s[68:69], 0, v242, s[68:69]
	v_addc_co_u32_e64 v242, s[70:71], 0, v242, s[70:71]
	v_addc_co_u32_e64 v242, s[72:73], 0, v242, s[72:73]
	v_addc_co_u32_e64 v242, s[74:75], 0, v242, s[74:75]
	s_nop 1
	v_add_u32_dpp v242, v242, v242 row_shr:1 row_mask:0xf bank_mask:0xf bound_ctrl:1
	s_nop 1
	v_add_u32_dpp v242, v242, v242 row_shr:2 row_mask:0xf bank_mask:0xf bound_ctrl:1
	s_nop 1
	v_add_u32_dpp v242, v242, v242 row_shr:4 row_mask:0xf bank_mask:0xf bound_ctrl:1
	s_nop 1
	v_add_u32_dpp v242, v242, v242 row_shr:8 row_mask:0xf bank_mask:0xf bound_ctrl:1
	s_nop 0
	v_readlane_b32 s42, v242, 15
	v_readlane_b32 s43, v242, 31
	s_add_i32 s42, s43, s42
	v_readlane_b32 s43, v242, 47
	s_add_i32 s42, s42, s43
	v_readlane_b32 s43, v242, 63
	s_add_i32 s42, s42, s43
	v_readfirstlane_b32 s62, v241
	s_cmpk_gt_i32 s42, 0xff
	s_cbranch_scc0 .Lsel1_fail
	s_mov_b32 s101, s62
	s_mov_b32 s59, s42
	s_mov_b32 s65, 0
	v_writelane_b32 v255, s65, 48
	s_cmpk_eq_i32 s42, 0x100
	s_cbranch_scc1 .Lsel1_exit
	s_branch .Lsel1_chk
.Lsel1_fail:
	s_mov_b32 s100, s62
.Lsel1_chk:
	s_sub_u32 s66, s100, s101
	s_cmp_le_u32 s66, 1
	s_cbranch_scc0 .Lsel1_top
.Lsel1_exit:
	v_mov_b32_e32 v16, s101

; template <int NB>
; __device__ __forceinline__ void bisect256(const unsigned (&x)[64], unsigned& tau_out, int& cge_out) {
;   unsigned tau = 0u;
;   int cge = 0;
;     ...
;     const unsigned cand = tau | (1u << bit);
; __device__ __forceinline__ void select_group(unsigned char* ws, int r0, const bf16_t* __restrict__ kib, int n, float* sc, SelPre& pre, int nr0, const bf16_t* __restrict__ nkib, int nn) {
;     ...
;     switch ((nreg + 7) >> 3) {
;       case 1: bisect256<1>(x, tau, cge); break;
;       case 2: bisect256<2>(x, tau, cge); break;
;       case 3: bisect256<3>(x, tau, cge); break;
;       case 4: bisect256<4>(x, tau, cge); break;
;       case 5: bisect256<5>(x, tau, cge); break;
;       case 6: bisect256<6>(x, tau, cge); break;
;       case 7: bisect256<7>(x, tau, cge); break;
;       default: bisect256<8>(x, tau, cge); break;
;     }
.LBB0_2948:
	s_cmp_gt_i32 s61, 4
	s_cbranch_scc0 .LBB0_2952
	s_mov_b32 s59, 0
	v_max_u32_e32 v240, v239, v238
	v_max3_u32 v240, v240, v237, v236
	v_max3_u32 v240, v240, v235, v234
	v_max3_u32 v240, v240, v233, v231
	v_max3_u32 v240, v240, v232, v230
	v_max3_u32 v240, v240, v229, v228
	v_max3_u32 v240, v240, v227, v226
	v_max3_u32 v240, v240, v225, v223
	v_max3_u32 v240, v240, v224, v222
	v_max3_u32 v240, v240, v221, v220
	v_max3_u32 v240, v240, v219, v218
	v_max3_u32 v240, v240, v217, v215
	v_max3_u32 v240, v240, v216, v214
	v_max3_u32 v240, v240, v213, v212
	v_max3_u32 v240, v240, v211, v210
	v_max3_u32 v240, v240, v207, v194
	v_max3_u32 v240, v240, v195, v193
	v_max3_u32 v240, v240, v192, v191
	v_max3_u32 v240, v240, v190, v189
	v_max3_u32 v240, v240, v188, v186
	s_nop 1
	v_max_u32_dpp v240, v240, v240 row_shr:1 row_mask:0xf bank_mask:0xf bound_ctrl:1
	s_nop 1
	v_max_u32_dpp v240, v240, v240 row_shr:2 row_mask:0xf bank_mask:0xf bound_ctrl:1
	s_nop 1
	v_max_u32_dpp v240, v240, v240 row_shr:4 row_mask:0xf bank_mask:0xf bound_ctrl:1
	s_nop 1
	v_max_u32_dpp v240, v240, v240 row_shr:8 row_mask:0xf bank_mask:0xf bound_ctrl:1
	s_nop 0
	v_readlane_b32 s42, v240, 15
	v_readlane_b32 s43, v240, 31
	s_max_u32 s42, s42, s43
	v_readlane_b32 s43, v240, 47
	s_max_u32 s42, s42, s43
	v_readlane_b32 s43, v240, 63
	s_max_u32 s42, s42, s43
	s_add_u32 s100, s42, 1
	s_cselect_b32 s100, -1, s100
	s_mov_b32 s101, 0
	s_mov_b32 s63, 0x1000000
	v_writelane_b32 v255, s63, 48
	v_writelane_b32 v255, s100, 49
	s_nop 1

; template <int NB>
; __device__ __forceinline__ void bisect256(const unsigned (&x)[64], unsigned& tau_out, int& cge_out) {
;     ...
;     unsigned cl = 0u;
; #pragma unroll
;     for (int blk = 0; blk < NB; ++blk) {
;       unsigned long long m0, m1, m2, m3, m4, m5, m6, m7;
;       asm volatile(
;           "v_cmp_ge_u32_e64 %1, %9, %17\n\tv_cmp_ge_u32_e64 %2, %10, %17\n\tv_cmp_ge_u32_e64 %3, %11, %17\n\tv_cmp_ge_u32_e64 %4, %12, %17\n\t"
;           "v_cmp_ge_u32_e64 %5, %13, %17\n\tv_cmp_ge_u32_e64 %6, %14, %17\n\tv_cmp_ge_u32_e64 %7, %15, %17\n\tv_cmp_ge_u32_e64 %8, %16, %17\n\t"
;           "v_addc_co_u32_e64 %0, %1, 0, %0, %1\n\tv_addc_co_u32_e64 %0, %2, 0, %0, %2\n\tv_addc_co_u32_e64 %0, %3, 0, %0, %3\n\t"
;           "v_addc_co_u32_e64 %0, %4, 0, %0, %4\n\tv_addc_co_u32_e64 %0, %5, 0, %0, %5\n\tv_addc_co_u32_e64 %0, %6, 0, %0, %6\n\t"
;           "v_addc_co_u32_e64 %0, %7, 0, %0, %7\n\tv_addc_co_u32_e64 %0, %8, 0, %0, %8"
;           : "+v"(cl), "=&s"(m0), "=&s"(m1), "=&s"(m2), "=&s"(m3), "=&s"(m4), "=&s"(m5), "=&s"(m6), "=&s"(m7)
;           : "v"(x[blk * 8 + 0]), "v"(x[blk * 8 + 1]), "v"(x[blk * 8 + 2]), "v"(x[blk * 8 + 3]), "v"(x[blk * 8 + 4]), "v"(x[blk * 8 + 5]),
;             "v"(x[blk * 8 + 6]), "v"(x[blk * 8 + 7]), "v"(cand));
;     }
;     cl += (unsigned)__builtin_amdgcn_update_dpp(0, (int)cl, 0x111, 0xf, 0xf, true);
;     cl += (unsigned)__builtin_amdgcn_update_dpp(0, (int)cl, 0x112, 0xf, 0xf, true);
;     cl += (unsigned)__builtin_amdgcn_update_dpp(0, (int)cl, 0x114, 0xf, 0xf, true);
;     cl += (unsigned)__builtin_amdgcn_update_dpp(0, (int)cl, 0x118, 0xf, 0xf, true);
;     const int cnt = __builtin_amdgcn_readlane((int)cl, 15) + __builtin_amdgcn_readlane((int)cl, 31) + __builtin_amdgcn_readlane((int)cl, 47) +
;                     __builtin_amdgcn_readlane((int)cl, 63);
;     if (cnt >= 256) { tau = cand; cge = cnt; }
;     if (cnt == 256) break;
;   }
.Lsel2_count:
	v_mov_b32_e32 v241, s62
	v_mov_b32_e32 v242, v17
	v_cmp_ge_u32_e64 s[42:43], v239, v241
	v_cmp_ge_u32_e64 s[62:63], v238, v241
	v_cmp_ge_u32_e64 s[64:65], v237, v241
	v_cmp_ge_u32_e64 s[66:67], v236, v241
	v_cmp_ge_u32_e64 s[68:69], v235, v241
	v_cmp_ge_u32_e64 s[70:71], v234, v241
	v_cmp_ge_u32_e64 s[72:73], v233, v241
	v_cmp_ge_u32_e64 s[74:75], v231, v241
	v_addc_co_u32_e64 v242, s[42:43], 0, v242, s[42:43]
	v_addc_co_u32_e64 v242, s[62:63], 0, v242, s[62:63]
	v_addc_co_u32_e64 v242, s[64:65], 0, v242, s[64:65]
	v_addc_co_u32_e64 v242, s[66:67], 0, v242, s[66:67]
	v_addc_co_u32_e64 v242, s[68:69], 0, v242, s[68:69]
	v_addc_co_u32_e64 v242, s[70:71], 0, v242, s[70:71]
	v_addc_co_u32_e64 v242, s[72:73], 0, v242, s[72:73]
	v_addc_co_u32_e64 v242, s[74:75], 0, v242, s[74:75]
	s_nop 0
	v_cmp_ge_u32_e64 s[42:43], v232, v241
	v_cmp_ge_u32_e64 s[62:63], v230, v241
	v_cmp_ge_u32_e64 s[64:65], v229, v241
	v_cmp_ge_u32_e64 s[66:67], v228, v241
	v_cmp_ge_u32_e64 s[68:69], v227, v241
	v_cmp_ge_u32_e64 s[70:71], v226, v241
	v_cmp_ge_u32_e64 s[72:73], v225, v241
	v_cmp_ge_u32_e64 s[74:75], v223, v241
	v_addc_co_u32_e64 v242, s[42:43], 0, v242, s[42:43]
	v_addc_co_u32_e64 v242, s[62:63], 0, v242, s[62:63]
	v_addc_co_u32_e64 v242, s[64:65], 0, v242, s[64:65]
	v_addc_co_u32_e64 v242, s[66:67], 0, v242, s[66:67]
	v_addc_co_u32_e64 v242, s[68:69], 0, v242, s[68:69]
	v_addc_co_u32_e64 v242, s[70:71], 0, v242, s[70:71]
	v_addc_co_u32_e64 v242, s[72:73], 0, v242, s[72:73]
	v_addc_co_u32_e64 v242, s[74:75], 0, v242, s[74:75]
	s_nop 0
	v_cmp_ge_u32_e64 s[42:43], v224, v241
	v_cmp_ge_u32_e64 s[62:63], v222, v241
	v_cmp_ge_u32_e64 s[64:65], v221, v241
	v_cmp_ge_u32_e64 s[66:67], v220, v241
	v_cmp_ge_u32_e64 s[68:69], v219, v241
	v_cmp_ge_u32_e64 s[70:71], v218, v241
	v_cmp_ge_u32_e64 s[72:73], v217, v241
	v_cmp_ge_u32_e64 s[74:75], v215, v241
	v_addc_co_u32_e64 v242, s[42:43], 0, v242, s[42:43]
	v_addc_co_u32_e64 v242, s[62:63], 0, v242, s[62:63]
	v_addc_co_u32_e64 v242, s[64:65], 0, v242, s[64:65]
	v_addc_co_u32_e64 v242, s[66:67], 0, v242, s[66:67]
	v_addc_co_u32_e64 v242, s[68:69], 0, v242, s[68:69]
	v_addc_co_u32_e64 v242, s[70:71], 0, v242, s[70:71]
	v_addc_co_u32_e64 v242, s[72:73], 0, v242, s[72:73]
	v_addc_co_u32_e64 v242, s[74:75], 0, v242, s[74:75]
	s_nop 0
	v_cmp_ge_u32_e64 s[42:43], v216, v241
	v_cmp_ge_u32_e64 s[62:63], v214, v241
	v_cmp_ge_u32_e64 s[64:65], v213, v241
	v_cmp_ge_u32_e64 s[66:67], v212, v241
	v_cmp_ge_u32_e64 s[68:69], v211, v241
	v_cmp_ge_u32_e64 s[70:71], v210, v241
	v_cmp_ge_u32_e64 s[72:73], v207, v241
	v_cmp_ge_u32_e64 s[74:75], v194, v241
	v_addc_co_u32_e64 v242, s[42:43], 0, v242, s[42:43]
	v_addc_co_u32_e64 v242, s[62:63], 0, v242, s[62:63]
	v_addc_co_u32_e64 v242, s[64:65], 0, v242, s[64:65]
	v_addc_co_u32_e64 v242, s[66:67], 0, v242, s[66:67]
	v_addc_co_u32_e64 v242, s[68:69], 0, v242, s[68:69]
	v_addc_co_u32_e64 v242, s[70:71], 0, v242, s[70:71]
	v_addc_co_u32_e64 v242, s[72:73], 0, v242, s[72:73]
	v_addc_co_u32_e64 v242, s[74:75], 0, v242, s[74:75]
	s_nop 0
	v_cmp_ge_u32_e64 s[42:43], v195, v241
	v_cmp_ge_u32_e64 s[62:63], v193, v241
	v_cmp_ge_u32_e64 s[64:65], v192, v241
	v_cmp_ge_u32_e64 s[66:67], v191, v241
	v_cmp_ge_u32_e64 s[68:69], v190, v241
	v_cmp_ge_u32_e64 s[70:71], v189, v241
	v_cmp_ge_u32_e64 s[72:73], v188, v241
	v_cmp_ge_u32_e64 s[74:75], v186, v241
	v_addc_co_u32_e64 v242, s[42:43], 0, v242, s[42:43]
	v_addc_co_u32_e64 v242, s[62:63], 0, v242, s[62:63]
	v_addc_co_u32_e64 v242, s[64:65], 0, v242, s[64:65]
	v_addc_co_u32_e64 v242, s[66:67], 0, v242, s[66:67]
	v_addc_co_u32_e64 v242, s[68:69], 0, v242, s[68:69]
	v_addc_co_u32_e64 v242, s[70:71], 0, v242, s[70:71]
	v_addc_co_u32_e64 v242, s[72:73], 0, v242, s[72:73]
	v_addc_co_u32_e64 v242, s[74:75], 0, v242, s[74:75]
	s_nop 1
	v_add_u32_dpp v242, v242, v242 row_shr:1 row_mask:0xf bank_mask:0xf bound_ctrl:1
	s_nop 1
	v_add_u32_dpp v242, v242, v242 row_shr:2 row_mask:0xf bank_mask:0xf bound_ctrl:1
	s_nop 1
	v_add_u32_dpp v242, v242, v242 row_shr:4 row_mask:0xf bank_mask:0xf bound_ctrl:1
	s_nop 1
	v_add_u32_dpp v242, v242, v242 row_shr:8 row_mask:0xf bank_mask:0xf bound_ctrl:1
	s_nop 0
	v_readlane_b32 s42, v242, 15
	v_readlane_b32 s43, v242, 31
	s_add_i32 s42, s43, s42
	v_readlane_b32 s43, v242, 47
	s_add_i32 s42, s42, s43
	v_readlane_b32 s43, v242, 63
	s_add_i32 s42, s42, s43
	v_readfirstlane_b32 s62, v241
	s_cmpk_gt_i32 s42, 0xff
	s_cbranch_scc0 .Lsel2_fail
	s_mov_b32 s101, s62
	s_mov_b32 s59, s42
	s_mov_b32 s65, 0
	v_writelane_b32 v255, s65, 48
	s_cmpk_eq_i32 s42, 0x100
	s_cbranch_scc1 .Lsel2_exit
	s_branch .Lsel2_chk

; template <int NB>
; __device__ __forceinline__ void bisect256(const unsigned (&x)[64], unsigned& tau_out, int& cge_out) {
;   unsigned tau = 0u;
;   int cge = 0;
;     ...
;     const unsigned cand = tau | (1u << bit);
;     ...
;   tau_out = tau;
;   cge_out = cge;
; }
.Lsel2_exit:
	v_mov_b32_e32 v16, s101
	s_branch .LBB0_2955
.LBB0_2952:
	s_cbranch_execz .LBB0_2955
	s_mov_b32 s59, 0
	v_max_u32_e32 v240, v239, v238
	v_max3_u32 v240, v240, v237, v236
	v_max3_u32 v240, v240, v235, v234
	v_max3_u32 v240, v240, v233, v231
	v_max3_u32 v240, v240, v232, v230
	v_max3_u32 v240, v240, v229, v228
	v_max3_u32 v240, v240, v227, v226
	v_max3_u32 v240, v240, v225, v223
	v_max3_u32 v240, v240, v224, v222
	v_max3_u32 v240, v240, v221, v220
	v_max3_u32 v240, v240, v219, v218
	v_max3_u32 v240, v240, v217, v215
	v_max3_u32 v240, v240, v216, v214
	v_max3_u32 v240, v240, v213, v212
	v_max3_u32 v240, v240, v211, v210
	v_max3_u32 v240, v240, v207, v194
	s_nop 1
	v_max_u32_dpp v240, v240, v240 row_shr:1 row_mask:0xf bank_mask:0xf bound_ctrl:1
	s_nop 1
	v_max_u32_dpp v240, v240, v240 row_shr:2 row_mask:0xf bank_mask:0xf bound_ctrl:1
	s_nop 1
	v_max_u32_dpp v240, v240, v240 row_shr:4 row_mask:0xf bank_mask:0xf bound_ctrl:1
	s_nop 1
	v_max_u32_dpp v240, v240, v240 row_shr:8 row_mask:0xf bank_mask:0xf bound_ctrl:1
	s_nop 0
	v_readlane_b32 s42, v240, 15
	v_readlane_b32 s43, v240, 31
	s_max_u32 s42, s42, s43
	v_readlane_b32 s43, v240, 47
	s_max_u32 s42, s42, s43
	v_readlane_b32 s43, v240, 63
	s_max_u32 s42, s42, s43
	s_add_u32 s100, s42, 1
	s_cselect_b32 s100, -1, s100
	s_mov_b32 s101, 0
	s_mov_b32 s63, 0x1000000
	v_writelane_b32 v255, s63, 48
	v_writelane_b32 v255, s100, 49
	s_nop 1

; template <int NB>
; __device__ __forceinline__ void bisect256(const unsigned (&x)[64], unsigned& tau_out, int& cge_out) {
;     ...
;     unsigned cl = 0u;
; #pragma unroll
;     for (int blk = 0; blk < NB; ++blk) {
;       unsigned long long m0, m1, m2, m3, m4, m5, m6, m7;
;       asm volatile(
;           "v_cmp_ge_u32_e64 %1, %9, %17\n\tv_cmp_ge_u32_e64 %2, %10, %17\n\tv_cmp_ge_u32_e64 %3, %11, %17\n\tv_cmp_ge_u32_e64 %4, %12, %17\n\t"
;           "v_cmp_ge_u32_e64 %5, %13, %17\n\tv_cmp_ge_u32_e64 %6, %14, %17\n\tv_cmp_ge_u32_e64 %7, %15, %17\n\tv_cmp_ge_u32_e64 %8, %16, %17\n\t"
;           "v_addc_co_u32_e64 %0, %1, 0, %0, %1\n\tv_addc_co_u32_e64 %0, %2, 0, %0, %2\n\tv_addc_co_u32_e64 %0, %3, 0, %0, %3\n\t"
;           "v_addc_co_u32_e64 %0, %4, 0, %0, %4\n\tv_addc_co_u32_e64 %0, %5, 0, %0, %5\n\tv_addc_co_u32_e64 %0, %6, 0, %0, %6\n\t"
;           "v_addc_co_u32_e64 %0, %7, 0, %0, %7\n\tv_addc_co_u32_e64 %0, %8, 0, %0, %8"
;           : "+v"(cl), "=&s"(m0), "=&s"(m1), "=&s"(m2), "=&s"(m3), "=&s"(m4), "=&s"(m5), "=&s"(m6), "=&s"(m7)
;           : "v"(x[blk * 8 + 0]), "v"(x[blk * 8 + 1]), "v"(x[blk * 8 + 2]), "v"(x[blk * 8 + 3]), "v"(x[blk * 8 + 4]), "v"(x[blk * 8 + 5]),
;             "v"(x[blk * 8 + 6]), "v"(x[blk * 8 + 7]), "v"(cand));
;     }
;     cl += (unsigned)__builtin_amdgcn_update_dpp(0, (int)cl, 0x111, 0xf, 0xf, true);
;     cl += (unsigned)__builtin_amdgcn_update_dpp(0, (int)cl, 0x112, 0xf, 0xf, true);
;     cl += (unsigned)__builtin_amdgcn_update_dpp(0, (int)cl, 0x114, 0xf, 0xf, true);
;     cl += (unsigned)__builtin_amdgcn_update_dpp(0, (int)cl, 0x118, 0xf, 0xf, true);
;     const int cnt = __builtin_amdgcn_readlane((int)cl, 15) + __builtin_amdgcn_readlane((int)cl, 31) + __builtin_amdgcn_readlane((int)cl, 47) +
;                     __builtin_amdgcn_readlane((int)cl, 63);
;     if (cnt >= 256) { tau = cand; cge = cnt; }
;     if (cnt == 256) break;
;   }
.Lsel3_count:
	v_mov_b32_e32 v241, s62
	v_mov_b32_e32 v242, v17
	v_cmp_ge_u32_e64 s[42:43], v239, v241
	v_cmp_ge_u32_e64 s[62:63], v238, v241
	v_cmp_ge_u32_e64 s[64:65], v237, v241
	v_cmp_ge_u32_e64 s[66:67], v236, v241
	v_cmp_ge_u32_e64 s[68:69], v235, v241
	v_cmp_ge_u32_e64 s[70:71], v234, v241
	v_cmp_ge_u32_e64 s[72:73], v233, v241
	v_cmp_ge_u32_e64 s[74:75], v231, v241
	v_addc_co_u32_e64 v242, s[42:43], 0, v242, s[42:43]
	v_addc_co_u32_e64 v242, s[62:63], 0, v242, s[62:63]
	v_addc_co_u32_e64 v242, s[64:65], 0, v242, s[64:65]
	v_addc_co_u32_e64 v242, s[66:67], 0, v242, s[66:67]
	v_addc_co_u32_e64 v242, s[68:69], 0, v242, s[68:69]
	v_addc_co_u32_e64 v242, s[70:71], 0, v242, s[70:71]
	v_addc_co_u32_e64 v242, s[72:73], 0, v242, s[72:73]
	v_addc_co_u32_e64 v242, s[74:75], 0, v242, s[74:75]
	s_nop 0
	v_cmp_ge_u32_e64 s[42:43], v232, v241
	v_cmp_ge_u32_e64 s[62:63], v230, v241
	v_cmp_ge_u32_e64 s[64:65], v229, v241
	v_cmp_ge_u32_e64 s[66:67], v228, v241
	v_cmp_ge_u32_e64 s[68:69], v227, v241
	v_cmp_ge_u32_e64 s[70:71], v226, v241
	v_cmp_ge_u32_e64 s[72:73], v225, v241
	v_cmp_ge_u32_e64 s[74:75], v223, v241
	v_addc_co_u32_e64 v242, s[42:43], 0, v242, s[42:43]
	v_addc_co_u32_e64 v242, s[62:63], 0, v242, s[62:63]
	v_addc_co_u32_e64 v242, s[64:65], 0, v242, s[64:65]
	v_addc_co_u32_e64 v242, s[66:67], 0, v242, s[66:67]
	v_addc_co_u32_e64 v242, s[68:69], 0, v242, s[68:69]
	v_addc_co_u32_e64 v242, s[70:71], 0, v242, s[70:71]
	v_addc_co_u32_e64 v242, s[72:73], 0, v242, s[72:73]
	v_addc_co_u32_e64 v242, s[74:75], 0, v242, s[74:75]
	s_nop 0
	v_cmp_ge_u32_e64 s[42:43], v224, v241
	v_cmp_ge_u32_e64 s[62:63], v222, v241
	v_cmp_ge_u32_e64 s[64:65], v221, v241
	v_cmp_ge_u32_e64 s[66:67], v220, v241
	v_cmp_ge_u32_e64 s[68:69], v219, v241
	v_cmp_ge_u32_e64 s[70:71], v218, v241
	v_cmp_ge_u32_e64 s[72:73], v217, v241
	v_cmp_ge_u32_e64 s[74:75], v215, v241
	v_addc_co_u32_e64 v242, s[42:43], 0, v242, s[42:43]
	v_addc_co_u32_e64 v242, s[62:63], 0, v242, s[62:63]
	v_addc_co_u32_e64 v242, s[64:65], 0, v242, s[64:65]
	v_addc_co_u32_e64 v242, s[66:67], 0, v242, s[66:67]
	v_addc_co_u32_e64 v242, s[68:69], 0, v242, s[68:69]
	v_addc_co_u32_e64 v242, s[70:71], 0, v242, s[70:71]
	v_addc_co_u32_e64 v242, s[72:73], 0, v242, s[72:73]
	v_addc_co_u32_e64 v242, s[74:75], 0, v242, s[74:75]
	s_nop 0
	v_cmp_ge_u32_e64 s[42:43], v216, v241
	v_cmp_ge_u32_e64 s[62:63], v214, v241
	v_cmp_ge_u32_e64 s[64:65], v213, v241
	v_cmp_ge_u32_e64 s[66:67], v212, v241
	v_cmp_ge_u32_e64 s[68:69], v211, v241
	v_cmp_ge_u32_e64 s[70:71], v210, v241
	v_cmp_ge_u32_e64 s[72:73], v207, v241
	v_cmp_ge_u32_e64 s[74:75], v194, v241
	v_addc_co_u32_e64 v242, s[42:43], 0, v242, s[42:43]
	v_addc_co_u32_e64 v242, s[62:63], 0, v242, s[62:63]
	v_addc_co_u32_e64 v242, s[64:65], 0, v242, s[64:65]
	v_addc_co_u32_e64 v242, s[66:67], 0, v242, s[66:67]
	v_addc_co_u32_e64 v242, s[68:69], 0, v242, s[68:69]
	v_addc_co_u32_e64 v242, s[70:71], 0, v242, s[70:71]
	v_addc_co_u32_e64 v242, s[72:73], 0, v242, s[72:73]
	v_addc_co_u32_e64 v242, s[74:75], 0, v242, s[74:75]
	s_nop 1
	v_add_u32_dpp v242, v242, v242 row_shr:1 row_mask:0xf bank_mask:0xf bound_ctrl:1
	s_nop 1
	v_add_u32_dpp v242, v242, v242 row_shr:2 row_mask:0xf bank_mask:0xf bound_ctrl:1
	s_nop 1
	v_add_u32_dpp v242, v242, v242 row_shr:4 row_mask:0xf bank_mask:0xf bound_ctrl:1
	s_nop 1
	v_add_u32_dpp v242, v242, v242 row_shr:8 row_mask:0xf bank_mask:0xf bound_ctrl:1
	s_nop 0
	v_readlane_b32 s42, v242, 15
	v_readlane_b32 s43, v242, 31
	s_add_i32 s42, s43, s42
	v_readlane_b32 s43, v242, 47
	s_add_i32 s42, s42, s43
	v_readlane_b32 s43, v242, 63
	s_add_i32 s42, s42, s43
	v_readfirstlane_b32 s62, v241
	s_cmpk_gt_i32 s42, 0xff
	s_cbranch_scc0 .Lsel3_fail
	s_mov_b32 s101, s62
	s_mov_b32 s59, s42
	s_mov_b32 s65, 0
	v_writelane_b32 v255, s65, 48
	s_cmpk_eq_i32 s42, 0x100
	s_cbranch_scc1 .Lsel3_exit
	s_branch .Lsel3_chk

; template <int NB>
; __device__ __forceinline__ void bisect256(const unsigned (&x)[64], unsigned& tau_out, int& cge_out) {
;   unsigned tau = 0u;
;   int cge = 0;
;     ...
;     const unsigned cand = tau | (1u << bit);
; __device__ __forceinline__ void select_group(unsigned char* ws, int r0, const bf16_t* __restrict__ kib, int n, float* sc, SelPre& pre, int nr0, const bf16_t* __restrict__ nkib, int nn) {
;     ...
;     switch ((nreg + 7) >> 3) {
;       case 1: bisect256<1>(x, tau, cge); break;
;       case 2: bisect256<2>(x, tau, cge); break;
;       case 3: bisect256<3>(x, tau, cge); break;
;       case 4: bisect256<4>(x, tau, cge); break;
;       case 5: bisect256<5>(x, tau, cge); break;
;       case 6: bisect256<6>(x, tau, cge); break;
;       case 7: bisect256<7>(x, tau, cge); break;
;       default: bisect256<8>(x, tau, cge); break;
;     }
.LBB0_2956:
	s_cmp_gt_i32 s61, 1
	s_cbranch_scc0 .LBB0_2961
	s_cmp_gt_i32 s61, 2
	s_cbranch_scc0 .LBB0_2962
	s_mov_b32 s59, 0
	v_max_u32_e32 v240, v239, v238
	v_max3_u32 v240, v240, v237, v236
	v_max3_u32 v240, v240, v235, v234
	v_max3_u32 v240, v240, v233, v231
	v_max3_u32 v240, v240, v232, v230
	v_max3_u32 v240, v240, v229, v228
	v_max3_u32 v240, v240, v227, v226
	v_max3_u32 v240, v240, v225, v223
	v_max3_u32 v240, v240, v224, v222
	v_max3_u32 v240, v240, v221, v220
	v_max3_u32 v240, v240, v219, v218
	v_max3_u32 v240, v240, v217, v215
	s_nop 1
	v_max_u32_dpp v240, v240, v240 row_shr:1 row_mask:0xf bank_mask:0xf bound_ctrl:1
	s_nop 1
	v_max_u32_dpp v240, v240, v240 row_shr:2 row_mask:0xf bank_mask:0xf bound_ctrl:1
	s_nop 1
	v_max_u32_dpp v240, v240, v240 row_shr:4 row_mask:0xf bank_mask:0xf bound_ctrl:1
	s_nop 1
	v_max_u32_dpp v240, v240, v240 row_shr:8 row_mask:0xf bank_mask:0xf bound_ctrl:1
	s_nop 0
	v_readlane_b32 s40, v240, 15
	v_readlane_b32 s41, v240, 31
	s_max_u32 s40, s40, s41
	v_readlane_b32 s41, v240, 47
	s_max_u32 s40, s40, s41
	v_readlane_b32 s41, v240, 63
	s_max_u32 s40, s40, s41
	s_add_u32 s100, s40, 1
	s_cselect_b32 s100, -1, s100
	s_mov_b32 s101, 0
	s_mov_b32 s43, 0x1000000
	v_writelane_b32 v255, s43, 48
	v_writelane_b32 v255, s100, 49
	s_nop 1

; template <int NB>
; __device__ __forceinline__ void bisect256(const unsigned (&x)[64], unsigned& tau_out, int& cge_out) {
;     ...
;     unsigned cl = 0u;
; #pragma unroll
;     for (int blk = 0; blk < NB; ++blk) {
;       unsigned long long m0, m1, m2, m3, m4, m5, m6, m7;
;       asm volatile(
;           "v_cmp_ge_u32_e64 %1, %9, %17\n\tv_cmp_ge_u32_e64 %2, %10, %17\n\tv_cmp_ge_u32_e64 %3, %11, %17\n\tv_cmp_ge_u32_e64 %4, %12, %17\n\t"
;           "v_cmp_ge_u32_e64 %5, %13, %17\n\tv_cmp_ge_u32_e64 %6, %14, %17\n\tv_cmp_ge_u32_e64 %7, %15, %17\n\tv_cmp_ge_u32_e64 %8, %16, %17\n\t"
;           "v_addc_co_u32_e64 %0, %1, 0, %0, %1\n\tv_addc_co_u32_e64 %0, %2, 0, %0, %2\n\tv_addc_co_u32_e64 %0, %3, 0, %0, %3\n\t"
;           "v_addc_co_u32_e64 %0, %4, 0, %0, %4\n\tv_addc_co_u32_e64 %0, %5, 0, %0, %5\n\tv_addc_co_u32_e64 %0, %6, 0, %0, %6\n\t"
;           "v_addc_co_u32_e64 %0, %7, 0, %0, %7\n\tv_addc_co_u32_e64 %0, %8, 0, %0, %8"
;           : "+v"(cl), "=&s"(m0), "=&s"(m1), "=&s"(m2), "=&s"(m3), "=&s"(m4), "=&s"(m5), "=&s"(m6), "=&s"(m7)
;           : "v"(x[blk * 8 + 0]), "v"(x[blk * 8 + 1]), "v"(x[blk * 8 + 2]), "v"(x[blk * 8 + 3]), "v"(x[blk * 8 + 4]), "v"(x[blk * 8 + 5]),
;             "v"(x[blk * 8 + 6]), "v"(x[blk * 8 + 7]), "v"(cand));
;     }
;     cl += (unsigned)__builtin_amdgcn_update_dpp(0, (int)cl, 0x111, 0xf, 0xf, true);
;     cl += (unsigned)__builtin_amdgcn_update_dpp(0, (int)cl, 0x112, 0xf, 0xf, true);
;     cl += (unsigned)__builtin_amdgcn_update_dpp(0, (int)cl, 0x114, 0xf, 0xf, true);
;     cl += (unsigned)__builtin_amdgcn_update_dpp(0, (int)cl, 0x118, 0xf, 0xf, true);
;     const int cnt = __builtin_amdgcn_readlane((int)cl, 15) + __builtin_amdgcn_readlane((int)cl, 31) + __builtin_amdgcn_readlane((int)cl, 47) +
;                     __builtin_amdgcn_readlane((int)cl, 63);
;     if (cnt >= 256) { tau = cand; cge = cnt; }
;     if (cnt == 256) break;
;   }
.Lsel4_count:
	v_mov_b32_e32 v241, s42
	v_mov_b32_e32 v242, v17
	v_cmp_ge_u32_e64 s[40:41], v239, v241
	v_cmp_ge_u32_e64 s[42:43], v238, v241
	v_cmp_ge_u32_e64 s[62:63], v237, v241
	v_cmp_ge_u32_e64 s[64:65], v236, v241
	v_cmp_ge_u32_e64 s[66:67], v235, v241
	v_cmp_ge_u32_e64 s[68:69], v234, v241
	v_cmp_ge_u32_e64 s[70:71], v233, v241
	v_cmp_ge_u32_e64 s[72:73], v231, v241
	v_addc_co_u32_e64 v242, s[40:41], 0, v242, s[40:41]
	v_addc_co_u32_e64 v242, s[42:43], 0, v242, s[42:43]
	v_addc_co_u32_e64 v242, s[62:63], 0, v242, s[62:63]
	v_addc_co_u32_e64 v242, s[64:65], 0, v242, s[64:65]
	v_addc_co_u32_e64 v242, s[66:67], 0, v242, s[66:67]
	v_addc_co_u32_e64 v242, s[68:69], 0, v242, s[68:69]
	v_addc_co_u32_e64 v242, s[70:71], 0, v242, s[70:71]
	v_addc_co_u32_e64 v242, s[72:73], 0, v242, s[72:73]
	s_nop 0
	v_cmp_ge_u32_e64 s[40:41], v232, v241
	v_cmp_ge_u32_e64 s[42:43], v230, v241
	v_cmp_ge_u32_e64 s[62:63], v229, v241
	v_cmp_ge_u32_e64 s[64:65], v228, v241
	v_cmp_ge_u32_e64 s[66:67], v227, v241
	v_cmp_ge_u32_e64 s[68:69], v226, v241
	v_cmp_ge_u32_e64 s[70:71], v225, v241
	v_cmp_ge_u32_e64 s[72:73], v223, v241
	v_addc_co_u32_e64 v242, s[40:41], 0, v242, s[40:41]
	v_addc_co_u32_e64 v242, s[42:43], 0, v242, s[42:43]
	v_addc_co_u32_e64 v242, s[62:63], 0, v242, s[62:63]
	v_addc_co_u32_e64 v242, s[64:65], 0, v242, s[64:65]
	v_addc_co_u32_e64 v242, s[66:67], 0, v242, s[66:67]
	v_addc_co_u32_e64 v242, s[68:69], 0, v242, s[68:69]
	v_addc_co_u32_e64 v242, s[70:71], 0, v242, s[70:71]
	v_addc_co_u32_e64 v242, s[72:73], 0, v242, s[72:73]
	s_nop 0
	v_cmp_ge_u32_e64 s[40:41], v224, v241
	v_cmp_ge_u32_e64 s[42:43], v222, v241
	v_cmp_ge_u32_e64 s[62:63], v221, v241
	v_cmp_ge_u32_e64 s[64:65], v220, v241
	v_cmp_ge_u32_e64 s[66:67], v219, v241
	v_cmp_ge_u32_e64 s[68:69], v218, v241
	v_cmp_ge_u32_e64 s[70:71], v217, v241
	v_cmp_ge_u32_e64 s[72:73], v215, v241
	v_addc_co_u32_e64 v242, s[40:41], 0, v242, s[40:41]
	v_addc_co_u32_e64 v242, s[42:43], 0, v242, s[42:43]
	v_addc_co_u32_e64 v242, s[62:63], 0, v242, s[62:63]
	v_addc_co_u32_e64 v242, s[64:65], 0, v242, s[64:65]
	v_addc_co_u32_e64 v242, s[66:67], 0, v242, s[66:67]
	v_addc_co_u32_e64 v242, s[68:69], 0, v242, s[68:69]
	v_addc_co_u32_e64 v242, s[70:71], 0, v242, s[70:71]
	v_addc_co_u32_e64 v242, s[72:73], 0, v242, s[72:73]
	s_nop 1
	v_add_u32_dpp v242, v242, v242 row_shr:1 row_mask:0xf bank_mask:0xf bound_ctrl:1
	s_nop 1
	v_add_u32_dpp v242, v242, v242 row_shr:2 row_mask:0xf bank_mask:0xf bound_ctrl:1
	s_nop 1
	v_add_u32_dpp v242, v242, v242 row_shr:4 row_mask:0xf bank_mask:0xf bound_ctrl:1
	s_nop 1
	v_add_u32_dpp v242, v242, v242 row_shr:8 row_mask:0xf bank_mask:0xf bound_ctrl:1
	s_nop 0
	v_readlane_b32 s40, v242, 15
	v_readlane_b32 s41, v242, 31
	s_add_i32 s40, s41, s40
	v_readlane_b32 s41, v242, 47
	s_add_i32 s40, s40, s41
	v_readlane_b32 s41, v242, 63
	s_add_i32 s40, s40, s41
	v_readfirstlane_b32 s42, v241
	s_cmpk_gt_i32 s40, 0xff
	s_cbranch_scc0 .Lsel4_fail
	s_mov_b32 s101, s42
	s_mov_b32 s59, s40
	s_mov_b32 s63, 0
	v_writelane_b32 v255, s63, 48
	s_cmpk_eq_i32 s40, 0x100
	s_cbranch_scc1 .Lsel4_exit
	s_branch .Lsel4_chk

; template <int NB>
; __device__ __forceinline__ void bisect256(const unsigned (&x)[64], unsigned& tau_out, int& cge_out) {
;   unsigned tau = 0u;
;   int cge = 0;
;     ...
;     const unsigned cand = tau | (1u << bit);
; __device__ __forceinline__ void select_group(unsigned char* ws, int r0, const bf16_t* __restrict__ kib, int n, float* sc, SelPre& pre, int nr0, const bf16_t* __restrict__ nkib, int nn) {
;     ...
;     switch ((nreg + 7) >> 3) {
;       case 1: bisect256<1>(x, tau, cge); break;
;       case 2: bisect256<2>(x, tau, cge); break;
;       case 3: bisect256<3>(x, tau, cge); break;
;       case 4: bisect256<4>(x, tau, cge); break;
;       case 5: bisect256<5>(x, tau, cge); break;
;       case 6: bisect256<6>(x, tau, cge); break;
;       case 7: bisect256<7>(x, tau, cge); break;
;       default: bisect256<8>(x, tau, cge); break;
;     }
.LBB0_2962:
	s_cbranch_execz .LBB0_2965
	s_mov_b32 s59, 0
	v_max_u32_e32 v240, v239, v238
	v_max3_u32 v240, v240, v237, v236
	v_max3_u32 v240, v240, v235, v234
	v_max3_u32 v240, v240, v233, v231
	v_max3_u32 v240, v240, v232, v230
	v_max3_u32 v240, v240, v229, v228
	v_max3_u32 v240, v240, v227, v226
	v_max3_u32 v240, v240, v225, v223
	s_nop 1
	v_max_u32_dpp v240, v240, v240 row_shr:1 row_mask:0xf bank_mask:0xf bound_ctrl:1
	s_nop 1
	v_max_u32_dpp v240, v240, v240 row_shr:2 row_mask:0xf bank_mask:0xf bound_ctrl:1
	s_nop 1
	v_max_u32_dpp v240, v240, v240 row_shr:4 row_mask:0xf bank_mask:0xf bound_ctrl:1
	s_nop 1
	v_max_u32_dpp v240, v240, v240 row_shr:8 row_mask:0xf bank_mask:0xf bound_ctrl:1
	s_nop 0
	v_readlane_b32 s40, v240, 15
	v_readlane_b32 s41, v240, 31
	s_max_u32 s40, s40, s41
	v_readlane_b32 s41, v240, 47
	s_max_u32 s40, s40, s41
	v_readlane_b32 s41, v240, 63
	s_max_u32 s40, s40, s41
	s_add_u32 s100, s40, 1
	s_cselect_b32 s100, -1, s100
	s_mov_b32 s101, 0
	s_mov_b32 s43, 0x1000000
	v_writelane_b32 v255, s43, 48
	v_writelane_b32 v255, s100, 49
	s_nop 1

; template <int NB>
; __device__ __forceinline__ void bisect256(const unsigned (&x)[64], unsigned& tau_out, int& cge_out) {
;     ...
;     unsigned cl = 0u;
; #pragma unroll
;     for (int blk = 0; blk < NB; ++blk) {
;       unsigned long long m0, m1, m2, m3, m4, m5, m6, m7;
;       asm volatile(
;           "v_cmp_ge_u32_e64 %1, %9, %17\n\tv_cmp_ge_u32_e64 %2, %10, %17\n\tv_cmp_ge_u32_e64 %3, %11, %17\n\tv_cmp_ge_u32_e64 %4, %12, %17\n\t"
;           "v_cmp_ge_u32_e64 %5, %13, %17\n\tv_cmp_ge_u32_e64 %6, %14, %17\n\tv_cmp_ge_u32_e64 %7, %15, %17\n\tv_cmp_ge_u32_e64 %8, %16, %17\n\t"
;           "v_addc_co_u32_e64 %0, %1, 0, %0, %1\n\tv_addc_co_u32_e64 %0, %2, 0, %0, %2\n\tv_addc_co_u32_e64 %0, %3, 0, %0, %3\n\t"
;           "v_addc_co_u32_e64 %0, %4, 0, %0, %4\n\tv_addc_co_u32_e64 %0, %5, 0, %0, %5\n\tv_addc_co_u32_e64 %0, %6, 0, %0, %6\n\t"
;           "v_addc_co_u32_e64 %0, %7, 0, %0, %7\n\tv_addc_co_u32_e64 %0, %8, 0, %0, %8"
;           : "+v"(cl), "=&s"(m0), "=&s"(m1), "=&s"(m2), "=&s"(m3), "=&s"(m4), "=&s"(m5), "=&s"(m6), "=&s"(m7)
;           : "v"(x[blk * 8 + 0]), "v"(x[blk * 8 + 1]), "v"(x[blk * 8 + 2]), "v"(x[blk * 8 + 3]), "v"(x[blk * 8 + 4]), "v"(x[blk * 8 + 5]),
;             "v"(x[blk * 8 + 6]), "v"(x[blk * 8 + 7]), "v"(cand));
;     }
;     cl += (unsigned)__builtin_amdgcn_update_dpp(0, (int)cl, 0x111, 0xf, 0xf, true);
;     cl += (unsigned)__builtin_amdgcn_update_dpp(0, (int)cl, 0x112, 0xf, 0xf, true);
;     cl += (unsigned)__builtin_amdgcn_update_dpp(0, (int)cl, 0x114, 0xf, 0xf, true);
;     cl += (unsigned)__builtin_amdgcn_update_dpp(0, (int)cl, 0x118, 0xf, 0xf, true);
;     const int cnt = __builtin_amdgcn_readlane((int)cl, 15) + __builtin_amdgcn_readlane((int)cl, 31) + __builtin_amdgcn_readlane((int)cl, 47) +
;                     __builtin_amdgcn_readlane((int)cl, 63);
;     if (cnt >= 256) { tau = cand; cge = cnt; }
;     if (cnt == 256) break;
;   }
.Lsel5_count:
	v_mov_b32_e32 v241, s42
	v_mov_b32_e32 v242, v17
	v_cmp_ge_u32_e64 s[40:41], v239, v241
	v_cmp_ge_u32_e64 s[42:43], v238, v241
	v_cmp_ge_u32_e64 s[62:63], v237, v241
	v_cmp_ge_u32_e64 s[64:65], v236, v241
	v_cmp_ge_u32_e64 s[66:67], v235, v241
	v_cmp_ge_u32_e64 s[68:69], v234, v241
	v_cmp_ge_u32_e64 s[70:71], v233, v241
	v_cmp_ge_u32_e64 s[72:73], v231, v241
	v_addc_co_u32_e64 v242, s[40:41], 0, v242, s[40:41]
	v_addc_co_u32_e64 v242, s[42:43], 0, v242, s[42:43]
	v_addc_co_u32_e64 v242, s[62:63], 0, v242, s[62:63]
	v_addc_co_u32_e64 v242, s[64:65], 0, v242, s[64:65]
	v_addc_co_u32_e64 v242, s[66:67], 0, v242, s[66:67]
	v_addc_co_u32_e64 v242, s[68:69], 0, v242, s[68:69]
	v_addc_co_u32_e64 v242, s[70:71], 0, v242, s[70:71]
	v_addc_co_u32_e64 v242, s[72:73], 0, v242, s[72:73]
	s_nop 0
	v_cmp_ge_u32_e64 s[40:41], v232, v241
	v_cmp_ge_u32_e64 s[42:43], v230, v241
	v_cmp_ge_u32_e64 s[62:63], v229, v241
	v_cmp_ge_u32_e64 s[64:65], v228, v241
	v_cmp_ge_u32_e64 s[66:67], v227, v241
	v_cmp_ge_u32_e64 s[68:69], v226, v241
	v_cmp_ge_u32_e64 s[70:71], v225, v241
	v_cmp_ge_u32_e64 s[72:73], v223, v241
	v_addc_co_u32_e64 v242, s[40:41], 0, v242, s[40:41]
	v_addc_co_u32_e64 v242, s[42:43], 0, v242, s[42:43]
	v_addc_co_u32_e64 v242, s[62:63], 0, v242, s[62:63]
	v_addc_co_u32_e64 v242, s[64:65], 0, v242, s[64:65]
	v_addc_co_u32_e64 v242, s[66:67], 0, v242, s[66:67]
	v_addc_co_u32_e64 v242, s[68:69], 0, v242, s[68:69]
	v_addc_co_u32_e64 v242, s[70:71], 0, v242, s[70:71]
	v_addc_co_u32_e64 v242, s[72:73], 0, v242, s[72:73]
	s_nop 1
	v_add_u32_dpp v242, v242, v242 row_shr:1 row_mask:0xf bank_mask:0xf bound_ctrl:1
	s_nop 1
	v_add_u32_dpp v242, v242, v242 row_shr:2 row_mask:0xf bank_mask:0xf bound_ctrl:1
	s_nop 1
	v_add_u32_dpp v242, v242, v242 row_shr:4 row_mask:0xf bank_mask:0xf bound_ctrl:1
	s_nop 1
	v_add_u32_dpp v242, v242, v242 row_shr:8 row_mask:0xf bank_mask:0xf bound_ctrl:1
	s_nop 0
	v_readlane_b32 s40, v242, 15
	v_readlane_b32 s41, v242, 31
	s_add_i32 s40, s41, s40
	v_readlane_b32 s41, v242, 47
	s_add_i32 s40, s40, s41
	v_readlane_b32 s41, v242, 63
	s_add_i32 s40, s40, s41
	v_readfirstlane_b32 s42, v241
	s_cmpk_gt_i32 s40, 0xff
	s_cbranch_scc0 .Lsel5_fail
	s_mov_b32 s101, s42
	s_mov_b32 s59, s40
	s_mov_b32 s63, 0
	v_writelane_b32 v255, s63, 48
	s_cmpk_eq_i32 s40, 0x100
	s_cbranch_scc1 .Lsel5_exit
	s_branch .Lsel5_chk

; template <int NB>
; __device__ __forceinline__ void bisect256(const unsigned (&x)[64], unsigned& tau_out, int& cge_out) {
;   unsigned tau = 0u;
;   int cge = 0;
;     ...
;     const unsigned cand = tau | (1u << bit);
;     unsigned cl = 0u;
; #pragma unroll
;     for (int blk = 0; blk < NB; ++blk) {
;       unsigned long long m0, m1, m2, m3, m4, m5, m6, m7;
;       asm volatile(
;           "v_cmp_ge_u32_e64 %1, %9, %17\n\tv_cmp_ge_u32_e64 %2, %10, %17\n\tv_cmp_ge_u32_e64 %3, %11, %17\n\tv_cmp_ge_u32_e64 %4, %12, %17\n\t"
;           "v_cmp_ge_u32_e64 %5, %13, %17\n\tv_cmp_ge_u32_e64 %6, %14, %17\n\tv_cmp_ge_u32_e64 %7, %15, %17\n\tv_cmp_ge_u32_e64 %8, %16, %17\n\t"
;           "v_addc_co_u32_e64 %0, %1, 0, %0, %1\n\tv_addc_co_u32_e64 %0, %2, 0, %0, %2\n\tv_addc_co_u32_e64 %0, %3, 0, %0, %3\n\t"
;           "v_addc_co_u32_e64 %0, %4, 0, %0, %4\n\tv_addc_co_u32_e64 %0, %5, 0, %0, %5\n\tv_addc_co_u32_e64 %0, %6, 0, %0, %6\n\t"
;           "v_addc_co_u32_e64 %0, %7, 0, %0, %7\n\tv_addc_co_u32_e64 %0, %8, 0, %0, %8"
;           : "+v"(cl), "=&s"(m0), "=&s"(m1), "=&s"(m2), "=&s"(m3), "=&s"(m4), "=&s"(m5), "=&s"(m6), "=&s"(m7)
;           : "v"(x[blk * 8 + 0]), "v"(x[blk * 8 + 1]), "v"(x[blk * 8 + 2]), "v"(x[blk * 8 + 3]), "v"(x[blk * 8 + 4]), "v"(x[blk * 8 + 5]),
;             "v"(x[blk * 8 + 6]), "v"(x[blk * 8 + 7]), "v"(cand));
;     }
;     cl += (unsigned)__builtin_amdgcn_update_dpp(0, (int)cl, 0x111, 0xf, 0xf, true);
;     cl += (unsigned)__builtin_amdgcn_update_dpp(0, (int)cl, 0x112, 0xf, 0xf, true);
;     cl += (unsigned)__builtin_amdgcn_update_dpp(0, (int)cl, 0x114, 0xf, 0xf, true);
;     cl += (unsigned)__builtin_amdgcn_update_dpp(0, (int)cl, 0x118, 0xf, 0xf, true);
;     const int cnt = __builtin_amdgcn_readlane((int)cl, 15) + __builtin_amdgcn_readlane((int)cl, 31) + __builtin_amdgcn_readlane((int)cl, 47) +
;                     __builtin_amdgcn_readlane((int)cl, 63);
;     if (cnt >= 256) { tau = cand; cge = cnt; }
; __device__ __forceinline__ void select_group(unsigned char* ws, int r0, const bf16_t* __restrict__ kib, int n, float* sc, SelPre& pre, int nr0, const bf16_t* __restrict__ nkib, int nn) {
;     ...
; #pragma unroll
;     for (int i = 0; i < 64; ++i) {
;       const unsigned ub = __float_as_uint(rowl[i * 64]);
;       const unsigned o = ub ^ ((unsigned)((int)ub >> 31) | 0x80000000u);
;       x[i] = (i * 64 < nl) ? o : 0u;
;     }
.LBB0_2967:
	s_waitcnt lgkmcnt(3)
	v_ashrrev_i32_e32 v240, 31, v170
	v_bitop3_b32 v170, v240, v170, s58 bitop3:0x36
	v_cndmask_b32_e64 v243, 0, v170, s[12:13]
	v_ashrrev_i32_e32 v170, 31, v171
	v_bitop3_b32 v170, v170, v171, s58 bitop3:0x36
	v_cndmask_b32_e64 v242, 0, v170, s[6:7]
	s_waitcnt lgkmcnt(2)
	v_ashrrev_i32_e32 v170, 31, v168
	v_bitop3_b32 v168, v170, v168, s58 bitop3:0x36
	v_cndmask_b32_e64 v241, 0, v168, s[8:9]
	v_ashrrev_i32_e32 v168, 31, v169
	v_bitop3_b32 v168, v168, v169, s58 bitop3:0x36
	v_cndmask_b32_e64 v240, 0, v168, s[2:3]
	s_waitcnt lgkmcnt(1)
	v_ashrrev_i32_e32 v168, 31, v166
	v_bitop3_b32 v166, v168, v166, s58 bitop3:0x36
	v_cndmask_b32_e64 v171, 0, v166, s[4:5]
	v_ashrrev_i32_e32 v166, 31, v167
	v_bitop3_b32 v166, v166, v167, s58 bitop3:0x36
	v_cndmask_b32_e64 v170, 0, v166, s[0:1]
	s_waitcnt lgkmcnt(0)
	v_ashrrev_i32_e32 v166, 31, v164
	v_bitop3_b32 v164, v166, v164, s58 bitop3:0x36
	v_cndmask_b32_e64 v169, 0, v164, s[14:15]
	v_ashrrev_i32_e32 v164, 31, v165
	v_bitop3_b32 v164, v164, v165, s58 bitop3:0x36
	v_cndmask_b32_e64 v168, 0, v164, s[10:11]
	s_and_b64 vcc, exec, s[38:39]
	s_cbranch_vccz .LBB0_2971
	s_mov_b32 s59, 0
	v_max_u32_e32 v164, v239, v238
	v_max3_u32 v164, v164, v237, v236
	v_max3_u32 v164, v164, v235, v234
	v_max3_u32 v164, v164, v233, v231
	v_max3_u32 v164, v164, v232, v230
	v_max3_u32 v164, v164, v229, v228
	v_max3_u32 v164, v164, v227, v226
	v_max3_u32 v164, v164, v225, v223
	v_max3_u32 v164, v164, v224, v222
	v_max3_u32 v164, v164, v221, v220
	v_max3_u32 v164, v164, v219, v218
	v_max3_u32 v164, v164, v217, v215
	v_max3_u32 v164, v164, v216, v214
	v_max3_u32 v164, v164, v213, v212
	v_max3_u32 v164, v164, v211, v210
	v_max3_u32 v164, v164, v207, v194
	v_max3_u32 v164, v164, v195, v193
	v_max3_u32 v164, v164, v192, v191
	v_max3_u32 v164, v164, v190, v189
	v_max3_u32 v164, v164, v188, v186
	v_max3_u32 v164, v164, v187, v185
	v_max3_u32 v164, v164, v184, v183
	v_max3_u32 v164, v164, v182, v181
	v_max3_u32 v164, v164, v180, v178
	v_max3_u32 v164, v164, v179, v177
	v_max3_u32 v164, v164, v176, v175
	v_max3_u32 v164, v164, v174, v173
	v_max3_u32 v164, v164, v172, v115
	v_max3_u32 v164, v164, v243, v242
	v_max3_u32 v164, v164, v241, v240
	v_max3_u32 v164, v164, v171, v170
	v_max3_u32 v164, v164, v169, v168
	s_nop 1
	v_max_u32_dpp v164, v164, v164 row_shr:1 row_mask:0xf bank_mask:0xf bound_ctrl:1
	s_nop 1
	v_max_u32_dpp v164, v164, v164 row_shr:2 row_mask:0xf bank_mask:0xf bound_ctrl:1
	s_nop 1
	v_max_u32_dpp v164, v164, v164 row_shr:4 row_mask:0xf bank_mask:0xf bound_ctrl:1
	s_nop 1
	v_max_u32_dpp v164, v164, v164 row_shr:8 row_mask:0xf bank_mask:0xf bound_ctrl:1
	s_nop 0
	v_readlane_b32 s0, v164, 15
	v_readlane_b32 s1, v164, 31
	s_max_u32 s0, s0, s1
	v_readlane_b32 s1, v164, 47
	s_max_u32 s0, s0, s1
	v_readlane_b32 s1, v164, 63
	s_max_u32 s0, s0, s1
	s_add_u32 s100, s0, 1
	s_cselect_b32 s100, -1, s100
	s_mov_b32 s101, 0
	s_mov_b32 s3, 0x1000000
	v_writelane_b32 v255, s3, 48
	v_writelane_b32 v255, s100, 49
	s_nop 1
.Lsel6_top:
	v_readlane_b32 s3, v255, 48
	s_cmp_eq_u32 s3, 0
	s_cbranch_scc1 .Lsel6_mid
	v_readlane_b32 s4, v255, 49
	s_lshl_b32 s5, s3, 3
	s_cmp_ge_u32 s3, 0x40000000
	s_cselect_b32 s5, 0, s5
	v_writelane_b32 v255, s5, 48
	s_sub_u32 s2, s4, s3
	s_cbranch_scc1 .Lsel6_goff
	s_cmp_gt_u32 s2, s101
	s_cbranch_scc1 .Lsel6_count
.Lsel6_goff:
	s_mov_b32 s5, 0
	v_writelane_b32 v255, s5, 48
.Lsel6_mid:
	s_sub_u32 s2, s100, s101
	s_lshr_b32 s2, s2, 1
	s_add_u32 s2, s2, s101
.Lsel6_count:
	v_mov_b32_e32 v165, s2
	v_mov_b32_e32 v166, v17
	v_cmp_ge_u32_e64 s[0:1], v239, v165
	v_cmp_ge_u32_e64 s[2:3], v238, v165
	v_cmp_ge_u32_e64 s[4:5], v237, v165
	v_cmp_ge_u32_e64 s[6:7], v236, v165
	v_cmp_ge_u32_e64 s[8:9], v235, v165
	v_cmp_ge_u32_e64 s[10:11], v234, v165
	v_cmp_ge_u32_e64 s[12:13], v233, v165
	v_cmp_ge_u32_e64 s[14:15], v231, v165
	v_addc_co_u32_e64 v166, s[0:1], 0, v166, s[0:1]
	v_addc_co_u32_e64 v166, s[2:3], 0, v166, s[2:3]
	v_addc_co_u32_e64 v166, s[4:5], 0, v166, s[4:5]
	v_addc_co_u32_e64 v166, s[6:7], 0, v166, s[6:7]
	v_addc_co_u32_e64 v166, s[8:9], 0, v166, s[8:9]
	v_addc_co_u32_e64 v166, s[10:11], 0, v166, s[10:11]
	v_addc_co_u32_e64 v166, s[12:13], 0, v166, s[12:13]
	v_addc_co_u32_e64 v166, s[14:15], 0, v166, s[14:15]
	s_nop 0
	v_cmp_ge_u32_e64 s[0:1], v232, v165
	v_cmp_ge_u32_e64 s[2:3], v230, v165
	v_cmp_ge_u32_e64 s[4:5], v229, v165
	v_cmp_ge_u32_e64 s[6:7], v228, v165
	v_cmp_ge_u32_e64 s[8:9], v227, v165
	v_cmp_ge_u32_e64 s[10:11], v226, v165
	v_cmp_ge_u32_e64 s[12:13], v225, v165
	v_cmp_ge_u32_e64 s[14:15], v223, v165
	v_addc_co_u32_e64 v166, s[0:1], 0, v166, s[0:1]
	v_addc_co_u32_e64 v166, s[2:3], 0, v166, s[2:3]
	v_addc_co_u32_e64 v166, s[4:5], 0, v166, s[4:5]
	v_addc_co_u32_e64 v166, s[6:7], 0, v166, s[6:7]
	v_addc_co_u32_e64 v166, s[8:9], 0, v166, s[8:9]
	v_addc_co_u32_e64 v166, s[10:11], 0, v166, s[10:11]
	v_addc_co_u32_e64 v166, s[12:13], 0, v166, s[12:13]
	v_addc_co_u32_e64 v166, s[14:15], 0, v166, s[14:15]
	s_nop 0
	v_cmp_ge_u32_e64 s[0:1], v224, v165
	v_cmp_ge_u32_e64 s[2:3], v222, v165
	v_cmp_ge_u32_e64 s[4:5], v221, v165
	v_cmp_ge_u32_e64 s[6:7], v220, v165
	v_cmp_ge_u32_e64 s[8:9], v219, v165
	v_cmp_ge_u32_e64 s[10:11], v218, v165
	v_cmp_ge_u32_e64 s[12:13], v217, v165
	v_cmp_ge_u32_e64 s[14:15], v215, v165
	v_addc_co_u32_e64 v166, s[0:1], 0, v166, s[0:1]
	v_addc_co_u32_e64 v166, s[2:3], 0, v166, s[2:3]
	v_addc_co_u32_e64 v166, s[4:5], 0, v166, s[4:5]
	v_addc_co_u32_e64 v166, s[6:7], 0, v166, s[6:7]
	v_addc_co_u32_e64 v166, s[8:9], 0, v166, s[8:9]
	v_addc_co_u32_e64 v166, s[10:11], 0, v166, s[10:11]
; template <int NB>
; __device__ __forceinline__ void bisect256(const unsigned (&x)[64], unsigned& tau_out, int& cge_out) {
;     ...
;     const unsigned cand = tau | (1u << bit);
;     unsigned cl = 0u;
; #pragma unroll
;     for (int blk = 0; blk < NB; ++blk) {
;       unsigned long long m0, m1, m2, m3, m4, m5, m6, m7;
;       asm volatile(
;           "v_cmp_ge_u32_e64 %1, %9, %17\n\tv_cmp_ge_u32_e64 %2, %10, %17\n\tv_cmp_ge_u32_e64 %3, %11, %17\n\tv_cmp_ge_u32_e64 %4, %12, %17\n\t"
;           "v_cmp_ge_u32_e64 %5, %13, %17\n\tv_cmp_ge_u32_e64 %6, %14, %17\n\tv_cmp_ge_u32_e64 %7, %15, %17\n\tv_cmp_ge_u32_e64 %8, %16, %17\n\t"
;           "v_addc_co_u32_e64 %0, %1, 0, %0, %1\n\tv_addc_co_u32_e64 %0, %2, 0, %0, %2\n\tv_addc_co_u32_e64 %0, %3, 0, %0, %3\n\t"
;           "v_addc_co_u32_e64 %0, %4, 0, %0, %4\n\tv_addc_co_u32_e64 %0, %5, 0, %0, %5\n\tv_addc_co_u32_e64 %0, %6, 0, %0, %6\n\t"
;           "v_addc_co_u32_e64 %0, %7, 0, %0, %7\n\tv_addc_co_u32_e64 %0, %8, 0, %0, %8"
;           : "+v"(cl), "=&s"(m0), "=&s"(m1), "=&s"(m2), "=&s"(m3), "=&s"(m4), "=&s"(m5), "=&s"(m6), "=&s"(m7)
;           : "v"(x[blk * 8 + 0]), "v"(x[blk * 8 + 1]), "v"(x[blk * 8 + 2]), "v"(x[blk * 8 + 3]), "v"(x[blk * 8 + 4]), "v"(x[blk * 8 + 5]),
;             "v"(x[blk * 8 + 6]), "v"(x[blk * 8 + 7]), "v"(cand));
;     }
;     cl += (unsigned)__builtin_amdgcn_update_dpp(0, (int)cl, 0x111, 0xf, 0xf, true);
;     cl += (unsigned)__builtin_amdgcn_update_dpp(0, (int)cl, 0x112, 0xf, 0xf, true);
;     cl += (unsigned)__builtin_amdgcn_update_dpp(0, (int)cl, 0x114, 0xf, 0xf, true);
;     cl += (unsigned)__builtin_amdgcn_update_dpp(0, (int)cl, 0x118, 0xf, 0xf, true);
;     const int cnt = __builtin_amdgcn_readlane((int)cl, 15) + __builtin_amdgcn_readlane((int)cl, 31) + __builtin_amdgcn_readlane((int)cl, 47) +
;                     __builtin_amdgcn_readlane((int)cl, 63);
;     if (cnt >= 256) { tau = cand; cge = cnt; }
;     if (cnt == 256) break;
;   }
;   tau_out = tau;
;   cge_out = cge;
	v_addc_co_u32_e64 v166, s[12:13], 0, v166, s[12:13]
	v_addc_co_u32_e64 v166, s[14:15], 0, v166, s[14:15]
	s_nop 0
	v_cmp_ge_u32_e64 s[0:1], v216, v165
	v_cmp_ge_u32_e64 s[2:3], v214, v165
	v_cmp_ge_u32_e64 s[4:5], v213, v165
	v_cmp_ge_u32_e64 s[6:7], v212, v165
	v_cmp_ge_u32_e64 s[8:9], v211, v165
	v_cmp_ge_u32_e64 s[10:11], v210, v165
	v_cmp_ge_u32_e64 s[12:13], v207, v165
	v_cmp_ge_u32_e64 s[14:15], v194, v165
	v_addc_co_u32_e64 v166, s[0:1], 0, v166, s[0:1]
	v_addc_co_u32_e64 v166, s[2:3], 0, v166, s[2:3]
	v_addc_co_u32_e64 v166, s[4:5], 0, v166, s[4:5]
	v_addc_co_u32_e64 v166, s[6:7], 0, v166, s[6:7]
	v_addc_co_u32_e64 v166, s[8:9], 0, v166, s[8:9]
	v_addc_co_u32_e64 v166, s[10:11], 0, v166, s[10:11]
	v_addc_co_u32_e64 v166, s[12:13], 0, v166, s[12:13]
	v_addc_co_u32_e64 v166, s[14:15], 0, v166, s[14:15]
	s_nop 0
	v_cmp_ge_u32_e64 s[0:1], v195, v165
	v_cmp_ge_u32_e64 s[2:3], v193, v165
	v_cmp_ge_u32_e64 s[4:5], v192, v165
	v_cmp_ge_u32_e64 s[6:7], v191, v165
	v_cmp_ge_u32_e64 s[8:9], v190, v165
	v_cmp_ge_u32_e64 s[10:11], v189, v165
	v_cmp_ge_u32_e64 s[12:13], v188, v165
	v_cmp_ge_u32_e64 s[14:15], v186, v165
	v_addc_co_u32_e64 v166, s[0:1], 0, v166, s[0:1]
	v_addc_co_u32_e64 v166, s[2:3], 0, v166, s[2:3]
	v_addc_co_u32_e64 v166, s[4:5], 0, v166, s[4:5]
	v_addc_co_u32_e64 v166, s[6:7], 0, v166, s[6:7]
	v_addc_co_u32_e64 v166, s[8:9], 0, v166, s[8:9]
	v_addc_co_u32_e64 v166, s[10:11], 0, v166, s[10:11]
	v_addc_co_u32_e64 v166, s[12:13], 0, v166, s[12:13]
	v_addc_co_u32_e64 v166, s[14:15], 0, v166, s[14:15]
	s_nop 0
	v_cmp_ge_u32_e64 s[0:1], v187, v165
	v_cmp_ge_u32_e64 s[2:3], v185, v165
	v_cmp_ge_u32_e64 s[4:5], v184, v165
	v_cmp_ge_u32_e64 s[6:7], v183, v165
	v_cmp_ge_u32_e64 s[8:9], v182, v165
	v_cmp_ge_u32_e64 s[10:11], v181, v165
	v_cmp_ge_u32_e64 s[12:13], v180, v165
	v_cmp_ge_u32_e64 s[14:15], v178, v165
	v_addc_co_u32_e64 v166, s[0:1], 0, v166, s[0:1]
	v_addc_co_u32_e64 v166, s[2:3], 0, v166, s[2:3]
	v_addc_co_u32_e64 v166, s[4:5], 0, v166, s[4:5]
	v_addc_co_u32_e64 v166, s[6:7], 0, v166, s[6:7]
	v_addc_co_u32_e64 v166, s[8:9], 0, v166, s[8:9]
	v_addc_co_u32_e64 v166, s[10:11], 0, v166, s[10:11]
	v_addc_co_u32_e64 v166, s[12:13], 0, v166, s[12:13]
	v_addc_co_u32_e64 v166, s[14:15], 0, v166, s[14:15]
	s_nop 0
	v_cmp_ge_u32_e64 s[0:1], v179, v165
	v_cmp_ge_u32_e64 s[2:3], v177, v165
	v_cmp_ge_u32_e64 s[4:5], v176, v165
	v_cmp_ge_u32_e64 s[6:7], v175, v165
	v_cmp_ge_u32_e64 s[8:9], v174, v165
	v_cmp_ge_u32_e64 s[10:11], v173, v165
	v_cmp_ge_u32_e64 s[12:13], v172, v165
	v_cmp_ge_u32_e64 s[14:15], v115, v165
	v_addc_co_u32_e64 v166, s[0:1], 0, v166, s[0:1]
	v_addc_co_u32_e64 v166, s[2:3], 0, v166, s[2:3]
	v_addc_co_u32_e64 v166, s[4:5], 0, v166, s[4:5]
	v_addc_co_u32_e64 v166, s[6:7], 0, v166, s[6:7]
	v_addc_co_u32_e64 v166, s[8:9], 0, v166, s[8:9]
	v_addc_co_u32_e64 v166, s[10:11], 0, v166, s[10:11]
	v_addc_co_u32_e64 v166, s[12:13], 0, v166, s[12:13]
	v_addc_co_u32_e64 v166, s[14:15], 0, v166, s[14:15]
	s_nop 0
	v_cmp_ge_u32_e64 s[0:1], v243, v165
	v_cmp_ge_u32_e64 s[2:3], v242, v165
	v_cmp_ge_u32_e64 s[4:5], v241, v165
	v_cmp_ge_u32_e64 s[6:7], v240, v165
	v_cmp_ge_u32_e64 s[8:9], v171, v165
	v_cmp_ge_u32_e64 s[10:11], v170, v165
	v_cmp_ge_u32_e64 s[12:13], v169, v165
	v_cmp_ge_u32_e64 s[14:15], v168, v165
	v_addc_co_u32_e64 v166, s[0:1], 0, v166, s[0:1]
	v_addc_co_u32_e64 v166, s[2:3], 0, v166, s[2:3]
	v_addc_co_u32_e64 v166, s[4:5], 0, v166, s[4:5]
	v_addc_co_u32_e64 v166, s[6:7], 0, v166, s[6:7]
	v_addc_co_u32_e64 v166, s[8:9], 0, v166, s[8:9]
	v_addc_co_u32_e64 v166, s[10:11], 0, v166, s[10:11]
	v_addc_co_u32_e64 v166, s[12:13], 0, v166, s[12:13]
	v_addc_co_u32_e64 v166, s[14:15], 0, v166, s[14:15]
	s_nop 1
	v_add_u32_dpp v166, v166, v166 row_shr:1 row_mask:0xf bank_mask:0xf bound_ctrl:1
	s_nop 1
	v_add_u32_dpp v166, v166, v166 row_shr:2 row_mask:0xf bank_mask:0xf bound_ctrl:1
	s_nop 1
	v_add_u32_dpp v166, v166, v166 row_shr:4 row_mask:0xf bank_mask:0xf bound_ctrl:1
	s_nop 1
	v_add_u32_dpp v166, v166, v166 row_shr:8 row_mask:0xf bank_mask:0xf bound_ctrl:1
	s_nop 0
	v_readlane_b32 s0, v166, 15
	v_readlane_b32 s1, v166, 31
	s_add_i32 s0, s1, s0
	v_readlane_b32 s1, v166, 47
	s_add_i32 s0, s0, s1
	v_readlane_b32 s1, v166, 63
	s_add_i32 s0, s0, s1
	v_readfirstlane_b32 s2, v165
	s_cmpk_gt_i32 s0, 0xff
	s_cbranch_scc0 .Lsel6_fail
	s_mov_b32 s101, s2
	s_mov_b32 s59, s0
	s_mov_b32 s5, 0
	v_writelane_b32 v255, s5, 48
	s_cmpk_eq_i32 s0, 0x100
	s_cbranch_scc1 .Lsel6_exit
	s_branch .Lsel6_chk
.Lsel6_fail:
	s_mov_b32 s100, s2
.Lsel6_chk:
	s_sub_u32 s6, s100, s101
	s_cmp_le_u32 s6, 1
	s_cbranch_scc0 .Lsel6_top
.Lsel6_exit:
	v_mov_b32_e32 v16, s101
	s_mov_b64 s[40:41], 0
.LBB0_2971:
	s_and_b64 vcc, exec, s[40:41]
	s_cbranch_vccz .LBB0_2974
	s_mov_b32 s59, 0
	v_max_u32_e32 v164, v239, v238
	v_max3_u32 v164, v164, v237, v236
	v_max3_u32 v164, v164, v235, v234
	v_max3_u32 v164, v164, v233, v231
	s_nop 1
	v_max_u32_dpp v164, v164, v164 row_shr:1 row_mask:0xf bank_mask:0xf bound_ctrl:1
	s_nop 1
	v_max_u32_dpp v164, v164, v164 row_shr:2 row_mask:0xf bank_mask:0xf bound_ctrl:1
	s_nop 1
	v_max_u32_dpp v164, v164, v164 row_shr:4 row_mask:0xf bank_mask:0xf bound_ctrl:1
	s_nop 1
	v_max_u32_dpp v164, v164, v164 row_shr:8 row_mask:0xf bank_mask:0xf bound_ctrl:1
	s_nop 0
	v_readlane_b32 s0, v164, 15
	v_readlane_b32 s1, v164, 31
	s_max_u32 s0, s0, s1
	v_readlane_b32 s1, v164, 47
	s_max_u32 s0, s0, s1
	v_readlane_b32 s1, v164, 63
	s_max_u32 s0, s0, s1
	s_add_u32 s100, s0, 1
	s_cselect_b32 s100, -1, s100
	s_mov_b32 s101, 0
	s_mov_b32 s3, 0x1000000
	v_writelane_b32 v255, s3, 48
	v_writelane_b32 v255, s100, 49
	s_nop 1

; template <int NB>
; __device__ __forceinline__ void bisect256(const unsigned (&x)[64], unsigned& tau_out, int& cge_out) {
;     ...
;     const unsigned cand = tau | (1u << bit);
;     unsigned cl = 0u;
; #pragma unroll
;     for (int blk = 0; blk < NB; ++blk) {
;       unsigned long long m0, m1, m2, m3, m4, m5, m6, m7;
;       asm volatile(
;           "v_cmp_ge_u32_e64 %1, %9, %17\n\tv_cmp_ge_u32_e64 %2, %10, %17\n\tv_cmp_ge_u32_e64 %3, %11, %17\n\tv_cmp_ge_u32_e64 %4, %12, %17\n\t"
;           "v_cmp_ge_u32_e64 %5, %13, %17\n\tv_cmp_ge_u32_e64 %6, %14, %17\n\tv_cmp_ge_u32_e64 %7, %15, %17\n\tv_cmp_ge_u32_e64 %8, %16, %17\n\t"
;           "v_addc_co_u32_e64 %0, %1, 0, %0, %1\n\tv_addc_co_u32_e64 %0, %2, 0, %0, %2\n\tv_addc_co_u32_e64 %0, %3, 0, %0, %3\n\t"
;           "v_addc_co_u32_e64 %0, %4, 0, %0, %4\n\tv_addc_co_u32_e64 %0, %5, 0, %0, %5\n\tv_addc_co_u32_e64 %0, %6, 0, %0, %6\n\t"
;           "v_addc_co_u32_e64 %0, %7, 0, %0, %7\n\tv_addc_co_u32_e64 %0, %8, 0, %0, %8"
;           : "+v"(cl), "=&s"(m0), "=&s"(m1), "=&s"(m2), "=&s"(m3), "=&s"(m4), "=&s"(m5), "=&s"(m6), "=&s"(m7)
;           : "v"(x[blk * 8 + 0]), "v"(x[blk * 8 + 1]), "v"(x[blk * 8 + 2]), "v"(x[blk * 8 + 3]), "v"(x[blk * 8 + 4]), "v"(x[blk * 8 + 5]),
;             "v"(x[blk * 8 + 6]), "v"(x[blk * 8 + 7]), "v"(cand));
;     }
;     cl += (unsigned)__builtin_amdgcn_update_dpp(0, (int)cl, 0x111, 0xf, 0xf, true);
;     cl += (unsigned)__builtin_amdgcn_update_dpp(0, (int)cl, 0x112, 0xf, 0xf, true);
;     cl += (unsigned)__builtin_amdgcn_update_dpp(0, (int)cl, 0x114, 0xf, 0xf, true);
;     cl += (unsigned)__builtin_amdgcn_update_dpp(0, (int)cl, 0x118, 0xf, 0xf, true);
;     const int cnt = __builtin_amdgcn_readlane((int)cl, 15) + __builtin_amdgcn_readlane((int)cl, 31) + __builtin_amdgcn_readlane((int)cl, 47) +
;                     __builtin_amdgcn_readlane((int)cl, 63);
;     if (cnt >= 256) { tau = cand; cge = cnt; }
;     if (cnt == 256) break;
;   }
.Lsel7_count:
	v_mov_b32_e32 v165, s2
	v_mov_b32_e32 v166, v17
	v_cmp_ge_u32_e64 s[0:1], v239, v165
	v_cmp_ge_u32_e64 s[2:3], v238, v165
	v_cmp_ge_u32_e64 s[4:5], v237, v165
	v_cmp_ge_u32_e64 s[6:7], v236, v165
	v_cmp_ge_u32_e64 s[8:9], v235, v165
	v_cmp_ge_u32_e64 s[10:11], v234, v165
	v_cmp_ge_u32_e64 s[12:13], v233, v165
	v_cmp_ge_u32_e64 s[14:15], v231, v165
	v_addc_co_u32_e64 v166, s[0:1], 0, v166, s[0:1]
	v_addc_co_u32_e64 v166, s[2:3], 0, v166, s[2:3]
	v_addc_co_u32_e64 v166, s[4:5], 0, v166, s[4:5]
	v_addc_co_u32_e64 v166, s[6:7], 0, v166, s[6:7]
	v_addc_co_u32_e64 v166, s[8:9], 0, v166, s[8:9]
	v_addc_co_u32_e64 v166, s[10:11], 0, v166, s[10:11]
	v_addc_co_u32_e64 v166, s[12:13], 0, v166, s[12:13]
	v_addc_co_u32_e64 v166, s[14:15], 0, v166, s[14:15]
	s_nop 1
	v_add_u32_dpp v166, v166, v166 row_shr:1 row_mask:0xf bank_mask:0xf bound_ctrl:1
	s_nop 1
	v_add_u32_dpp v166, v166, v166 row_shr:2 row_mask:0xf bank_mask:0xf bound_ctrl:1
	s_nop 1
	v_add_u32_dpp v166, v166, v166 row_shr:4 row_mask:0xf bank_mask:0xf bound_ctrl:1
	s_nop 1
	v_add_u32_dpp v166, v166, v166 row_shr:8 row_mask:0xf bank_mask:0xf bound_ctrl:1
	s_nop 0
	v_readlane_b32 s0, v166, 15
	v_readlane_b32 s1, v166, 31
	s_add_i32 s0, s1, s0
	v_readlane_b32 s1, v166, 47
	s_add_i32 s0, s0, s1
	v_readlane_b32 s1, v166, 63
	s_add_i32 s0, s0, s1
	v_readfirstlane_b32 s2, v165
	s_cmpk_gt_i32 s0, 0xff
	s_cbranch_scc0 .Lsel7_fail
	s_mov_b32 s101, s2
	s_mov_b32 s59, s0
	s_mov_b32 s5, 0
	v_writelane_b32 v255, s5, 48
	s_cmpk_eq_i32 s0, 0x100
	s_cbranch_scc1 .Lsel7_exit
	s_branch .Lsel7_chk
